# v47 + 64-byte alignment of the 13 GEMM K-loop heads and the diff attention step loop head (code placement)
# baseline (speedup 1.0000x reference)
;     __device__ __forceinline__ size_t aoff(const Unit& u, size_t ts, int) const { return (size_t)u.pm * ts; }
;     __device__ __forceinline__ size_t boff(const Unit& u, size_t ts, int) const { return (size_t)u.pn * ts; }
;     __device__ __forceinline__ size_t aoff(const Unit& u, size_t ts, int K) const { return (size_t)(u.pm & 15) * ts + (size_t)(u.pm >> 4) * K * 2; }
;     __device__ __forceinline__ size_t boff(const Unit& u, size_t ts, int K) const { return (size_t)u.pn * ts + (size_t)(u.pm >> 4) * K * 2; }
; template <class Epi, class Sched, bool ALIGN_EPI = false, bool SP2 = false>
; __device__ __forceinline__ void gemm_phase(PG8_LAS unsigned char* lds, const Gemm g, const Sched& S, const Epi& E) {
;     ...
;         const bool has_next = S.next(ui + 1, nxt);
;         const char* nA = has_next ? (const char*)g.A + S.aoff(nxt, tstepA, K) : cA; const char* nB = has_next ? (const char*)g.Bt + S.boff(nxt, tstepB, K) : cB;
;     ...
; #pragma unroll
;         for (int a = 0; a < 2; ++a)
; #pragma unroll
;             for (int b = 0; b < 2; ++b)
; #pragma unroll
;                 for (int m = 0; m < 4; ++m)
; #pragma unroll
;                     for (int n = 0; n < 2; ++n) acc[a][b][m][n] = (f32x4){0.f, 0.f, 0.f, 0.f};
.LBB0_163:
	s_ashr_i32 s29, s28, 31
	s_lshl_b64 s[30:31], s[28:29], 17
	s_add_u32 s30, s26, s30
	s_addc_u32 s31, s27, s31
	s_ashr_i32 s23, s22, 31
	s_lshl_b64 s[34:35], s[22:23], 17
	v_readlane_b32 s24, v251, 59
	v_readlane_b32 s25, v251, 60
	s_add_u32 s34, s24, s34
	v_mov_b32_e32 v127, 0
	s_addc_u32 s35, s25, s35
	s_andn2_b64 vcc, exec, s[10:11]
	v_mov_b32_e32 v126, v127
	v_mov_b32_e32 v125, v127
	v_mov_b32_e32 v124, v127
	v_mov_b32_e32 v123, v127
	v_mov_b32_e32 v122, v127
	v_mov_b32_e32 v121, v127
	v_mov_b32_e32 v120, v127
	v_mov_b32_e32 v111, v127
	v_mov_b32_e32 v110, v127
	v_mov_b32_e32 v109, v127
	v_mov_b32_e32 v108, v127
	v_mov_b32_e32 v107, v127
	v_mov_b32_e32 v106, v127
	v_mov_b32_e32 v105, v127
	v_mov_b32_e32 v104, v127
	v_mov_b32_e32 v95, v127
	v_mov_b32_e32 v94, v127
	v_mov_b32_e32 v93, v127
	v_mov_b32_e32 v92, v127
	v_mov_b32_e32 v91, v127
	v_mov_b32_e32 v90, v127
	v_mov_b32_e32 v89, v127
	v_mov_b32_e32 v88, v127
	v_mov_b32_e32 v79, v127
	v_mov_b32_e32 v78, v127
	v_mov_b32_e32 v77, v127
	v_mov_b32_e32 v76, v127
	v_mov_b32_e32 v75, v127
	v_mov_b32_e32 v74, v127
	v_mov_b32_e32 v73, v127
	v_mov_b32_e32 v72, v127
	v_mov_b32_e32 v119, v127
	v_mov_b32_e32 v118, v127
	v_mov_b32_e32 v117, v127
	v_mov_b32_e32 v116, v127
	v_mov_b32_e32 v115, v127
	v_mov_b32_e32 v114, v127
	v_mov_b32_e32 v113, v127
	v_mov_b32_e32 v112, v127
	v_mov_b32_e32 v103, v127
	v_mov_b32_e32 v102, v127
	v_mov_b32_e32 v101, v127
	v_mov_b32_e32 v100, v127
	v_mov_b32_e32 v99, v127
	v_mov_b32_e32 v98, v127
	v_mov_b32_e32 v97, v127
	v_mov_b32_e32 v96, v127
	v_mov_b32_e32 v87, v127
	v_mov_b32_e32 v86, v127
	v_mov_b32_e32 v85, v127
	v_mov_b32_e32 v84, v127
	v_mov_b32_e32 v83, v127
	v_mov_b32_e32 v82, v127
	v_mov_b32_e32 v81, v127
	v_mov_b32_e32 v80, v127
	v_mov_b32_e32 v71, v127
	v_mov_b32_e32 v70, v127
	v_mov_b32_e32 v69, v127
	v_mov_b32_e32 v68, v127
	v_mov_b32_e32 v67, v127
	v_mov_b32_e32 v66, v127
	v_mov_b32_e32 v65, v127
	v_mov_b32_e32 v64, v127
	v_mov_b32_e32 v63, v127
	v_mov_b32_e32 v62, v127
	v_mov_b32_e32 v61, v127
	v_mov_b32_e32 v60, v127
	v_mov_b32_e32 v59, v127
	v_mov_b32_e32 v58, v127
	v_mov_b32_e32 v57, v127
	v_mov_b32_e32 v56, v127
	v_mov_b32_e32 v47, v127
	v_mov_b32_e32 v46, v127
	v_mov_b32_e32 v45, v127
	v_mov_b32_e32 v44, v127
	v_mov_b32_e32 v43, v127
	v_mov_b32_e32 v42, v127
	v_mov_b32_e32 v41, v127
	v_mov_b32_e32 v40, v127
	v_mov_b32_e32 v31, v127
	v_mov_b32_e32 v30, v127
	v_mov_b32_e32 v29, v127
	v_mov_b32_e32 v28, v127
	v_mov_b32_e32 v27, v127
	v_mov_b32_e32 v26, v127
	v_mov_b32_e32 v25, v127
	v_mov_b32_e32 v24, v127
	v_mov_b32_e32 v15, v127
	v_mov_b32_e32 v14, v127
	v_mov_b32_e32 v13, v127
	v_mov_b32_e32 v12, v127
	v_mov_b32_e32 v11, v127
	v_mov_b32_e32 v10, v127
	v_mov_b32_e32 v9, v127
	v_mov_b32_e32 v8, v127
	v_mov_b32_e32 v55, v127
	v_mov_b32_e32 v54, v127
	v_mov_b32_e32 v53, v127
	v_mov_b32_e32 v52, v127
	v_mov_b32_e32 v51, v127
	v_mov_b32_e32 v50, v127
	v_mov_b32_e32 v49, v127
	v_mov_b32_e32 v48, v127
	v_mov_b32_e32 v39, v127
	v_mov_b32_e32 v38, v127
	v_mov_b32_e32 v37, v127
	v_mov_b32_e32 v36, v127
	v_mov_b32_e32 v35, v127
	v_mov_b32_e32 v34, v127
	v_mov_b32_e32 v33, v127
	v_mov_b32_e32 v32, v127
	v_mov_b32_e32 v23, v127
	v_mov_b32_e32 v22, v127
	v_mov_b32_e32 v21, v127
	v_mov_b32_e32 v20, v127
	v_mov_b32_e32 v19, v127
	v_mov_b32_e32 v18, v127
	v_mov_b32_e32 v17, v127
	v_mov_b32_e32 v16, v127
	v_mov_b32_e32 v7, v127
	v_mov_b32_e32 v6, v127
	v_mov_b32_e32 v5, v127
	v_mov_b32_e32 v4, v127
	v_mov_b32_e32 v3, v127
	v_mov_b32_e32 v2, v127
	v_mov_b32_e32 v1, v127
	v_mov_b32_e32 v0, v127
	s_cbranch_vccnz .LBB0_166
	s_and_b64 s[42:43], s[20:21], exec
	s_cselect_b32 s19, s31, s39
	s_cselect_b32 s23, s30, s38
	s_cselect_b32 s29, s35, s41
	s_cselect_b32 s58, s34, s40
	s_add_u32 s38, s38, 0x10080
	s_addc_u32 s39, s39, 0
	s_add_u32 s59, s40, 0x100
	v_mov_b32_e32 v0, 0
	s_addc_u32 s60, s41, 0
	s_mov_b32 s40, 0
	v_mov_b32_e32 v1, v0
	v_mov_b32_e32 v2, v0
	v_mov_b32_e32 v3, v0
	v_mov_b32_e32 v4, v0
	v_mov_b32_e32 v5, v0
	v_mov_b32_e32 v6, v0
	v_mov_b32_e32 v7, v0
	v_mov_b32_e32 v16, v0
	v_mov_b32_e32 v17, v0
	v_mov_b32_e32 v18, v0
	v_mov_b32_e32 v19, v0
	v_mov_b32_e32 v20, v0
	v_mov_b32_e32 v21, v0
	v_mov_b32_e32 v22, v0
	v_mov_b32_e32 v23, v0
	v_mov_b32_e32 v32, v0
	v_mov_b32_e32 v33, v0
	v_mov_b32_e32 v34, v0
	v_mov_b32_e32 v35, v0
	v_mov_b32_e32 v36, v0
	v_mov_b32_e32 v37, v0
	v_mov_b32_e32 v38, v0
	v_mov_b32_e32 v39, v0
	v_mov_b32_e32 v48, v0
	v_mov_b32_e32 v49, v0
	v_mov_b32_e32 v50, v0
	v_mov_b32_e32 v51, v0
	v_mov_b32_e32 v52, v0
	v_mov_b32_e32 v53, v0
	v_mov_b32_e32 v54, v0
	v_mov_b32_e32 v55, v0
	v_mov_b32_e32 v8, v0
	v_mov_b32_e32 v9, v0
	v_mov_b32_e32 v10, v0
	v_mov_b32_e32 v11, v0
	v_mov_b32_e32 v12, v0
	v_mov_b32_e32 v13, v0
	v_mov_b32_e32 v14, v0
	v_mov_b32_e32 v15, v0
	v_mov_b32_e32 v24, v0
	v_mov_b32_e32 v25, v0
	v_mov_b32_e32 v26, v0
	v_mov_b32_e32 v27, v0
	v_mov_b32_e32 v28, v0
	v_mov_b32_e32 v29, v0
	v_mov_b32_e32 v30, v0
	v_mov_b32_e32 v31, v0
	v_mov_b32_e32 v40, v0
	v_mov_b32_e32 v41, v0
	v_mov_b32_e32 v42, v0
	v_mov_b32_e32 v43, v0
	v_mov_b32_e32 v44, v0
	v_mov_b32_e32 v45, v0
	v_mov_b32_e32 v46, v0
	v_mov_b32_e32 v47, v0
	v_mov_b32_e32 v56, v0
	v_mov_b32_e32 v57, v0
	v_mov_b32_e32 v58, v0
	v_mov_b32_e32 v59, v0
	v_mov_b32_e32 v60, v0
	v_mov_b32_e32 v61, v0
	v_mov_b32_e32 v62, v0
	v_mov_b32_e32 v63, v0
	v_mov_b32_e32 v64, v0
	v_mov_b32_e32 v65, v0
	v_mov_b32_e32 v66, v0
	v_mov_b32_e32 v67, v0
	v_mov_b32_e32 v68, v0
	v_mov_b32_e32 v69, v0
	v_mov_b32_e32 v70, v0
	v_mov_b32_e32 v71, v0
	v_mov_b32_e32 v80, v0
	v_mov_b32_e32 v81, v0
	v_mov_b32_e32 v82, v0
	v_mov_b32_e32 v83, v0
	v_mov_b32_e32 v84, v0
	v_mov_b32_e32 v85, v0
	v_mov_b32_e32 v86, v0
	v_mov_b32_e32 v87, v0
	v_mov_b32_e32 v96, v0
	v_mov_b32_e32 v97, v0
	v_mov_b32_e32 v98, v0
	v_mov_b32_e32 v99, v0
	v_mov_b32_e32 v100, v0
	v_mov_b32_e32 v101, v0
	v_mov_b32_e32 v102, v0
	v_mov_b32_e32 v103, v0
	v_mov_b32_e32 v112, v0
	v_mov_b32_e32 v113, v0
	v_mov_b32_e32 v114, v0
	v_mov_b32_e32 v115, v0
	v_mov_b32_e32 v116, v0
	v_mov_b32_e32 v117, v0
	v_mov_b32_e32 v118, v0
	v_mov_b32_e32 v119, v0
	v_mov_b32_e32 v72, v0
	v_mov_b32_e32 v73, v0
	v_mov_b32_e32 v74, v0
	v_mov_b32_e32 v75, v0
	v_mov_b32_e32 v76, v0
	v_mov_b32_e32 v77, v0
	v_mov_b32_e32 v78, v0
	v_mov_b32_e32 v79, v0
	v_mov_b32_e32 v88, v0
	v_mov_b32_e32 v89, v0
	v_mov_b32_e32 v90, v0
	v_mov_b32_e32 v91, v0
	v_mov_b32_e32 v92, v0
	v_mov_b32_e32 v93, v0
	v_mov_b32_e32 v94, v0
	v_mov_b32_e32 v95, v0
	v_mov_b32_e32 v104, v0
	v_mov_b32_e32 v105, v0
	v_mov_b32_e32 v106, v0
	v_mov_b32_e32 v107, v0
	v_mov_b32_e32 v108, v0
	v_mov_b32_e32 v109, v0
	v_mov_b32_e32 v110, v0
	v_mov_b32_e32 v111, v0
	v_mov_b32_e32 v120, v0
	v_mov_b32_e32 v121, v0
	v_mov_b32_e32 v122, v0
	v_mov_b32_e32 v123, v0
	v_mov_b32_e32 v124, v0
	v_mov_b32_e32 v125, v0
	v_mov_b32_e32 v126, v0
	v_mov_b32_e32 v127, v0
	.p2alignl 6, 3212836864

;     __device__ __forceinline__ size_t aoff(const Unit& u, size_t ts, int) const { return (size_t)u.pm * ts; }
;     __device__ __forceinline__ size_t boff(const Unit& u, size_t ts, int) const { return (size_t)u.pn * ts; }
;     __device__ __forceinline__ size_t aoff(const Unit& u, size_t ts, int K) const { return (size_t)(u.pm & 15) * ts + (size_t)(u.pm >> 4) * K * 2; }
;     __device__ __forceinline__ size_t boff(const Unit& u, size_t ts, int K) const { return (size_t)u.pn * ts + (size_t)(u.pm >> 4) * K * 2; }
; template <class Epi, class Sched, bool ALIGN_EPI = false, bool SP2 = false>
; __device__ __forceinline__ void gemm_phase(PG8_LAS unsigned char* lds, const Gemm g, const Sched& S, const Epi& E) {
;     ...
;         const bool has_next = S.next(ui + 1, nxt);
;         const char* nA = has_next ? (const char*)g.A + S.aoff(nxt, tstepA, K) : cA; const char* nB = has_next ? (const char*)g.Bt + S.boff(nxt, tstepB, K) : cB;
;     ...
; #pragma unroll
;         for (int a = 0; a < 2; ++a)
; #pragma unroll
;             for (int b = 0; b < 2; ++b)
; #pragma unroll
;                 for (int m = 0; m < 4; ++m)
; #pragma unroll
;                     for (int n = 0; n < 2; ++n) acc[a][b][m][n] = (f32x4){0.f, 0.f, 0.f, 0.f};
.LBB0_299:
	s_ashr_i32 s85, s84, 31
	s_lshl_b64 s[48:49], s[84:85], 19
	s_add_u32 s86, s72, s48
	s_addc_u32 s87, s73, s49
	s_ashr_i32 s83, s82, 31
	s_lshl_b64 s[48:49], s[82:83], 19
	v_readlane_b32 s4, v251, 48
	v_readlane_b32 s5, v251, 49
	s_add_u32 s88, s4, s48
	s_addc_u32 s89, s5, s49
	s_andn2_b64 vcc, exec, s[68:69]
	s_mov_b32 s48, 0
	s_cbranch_vccnz .LBB0_423
	s_and_b64 s[58:59], s[38:39], exec
	s_cselect_b32 s29, s87, s43
	s_cselect_b32 s33, s86, s42
	s_cselect_b32 s41, s89, s47
	s_cselect_b32 s45, s88, s46
	s_add_u32 s42, s42, 0x40080
	s_addc_u32 s43, s43, 0
	s_add_u32 s55, s46, 0x100
	v_mov_b32_e32 v0, 0
	s_addc_u32 s58, s47, 0
	v_mov_b32_e32 v1, v0
	v_mov_b32_e32 v2, v0
	v_mov_b32_e32 v3, v0
	v_mov_b32_e32 v4, v0
	v_mov_b32_e32 v5, v0
	v_mov_b32_e32 v6, v0
	v_mov_b32_e32 v7, v0
	v_mov_b32_e32 v16, v0
	v_mov_b32_e32 v17, v0
	v_mov_b32_e32 v18, v0
	v_mov_b32_e32 v19, v0
	v_mov_b32_e32 v20, v0
	v_mov_b32_e32 v21, v0
	s_waitcnt lgkmcnt(0)
	v_mov_b32_e32 v22, v0
	v_mov_b32_e32 v23, v0
	v_mov_b32_e32 v32, v0
	v_mov_b32_e32 v33, v0
	v_mov_b32_e32 v34, v0
	v_mov_b32_e32 v35, v0
	v_mov_b32_e32 v36, v0
	v_mov_b32_e32 v37, v0
	v_mov_b32_e32 v38, v0
	v_mov_b32_e32 v39, v0
	v_mov_b32_e32 v48, v0
	v_mov_b32_e32 v49, v0
	v_mov_b32_e32 v50, v0
	v_mov_b32_e32 v51, v0
	v_mov_b32_e32 v52, v0
	v_mov_b32_e32 v53, v0
	v_mov_b32_e32 v54, v0
	v_mov_b32_e32 v55, v0
	v_mov_b32_e32 v8, v0
	v_mov_b32_e32 v9, v0
	v_mov_b32_e32 v10, v0
	v_mov_b32_e32 v11, v0
	v_mov_b32_e32 v12, v0
	v_mov_b32_e32 v13, v0
	v_mov_b32_e32 v14, v0
	v_mov_b32_e32 v15, v0
	v_mov_b32_e32 v24, v0
	v_mov_b32_e32 v25, v0
	v_mov_b32_e32 v26, v0
	v_mov_b32_e32 v27, v0
	v_mov_b32_e32 v28, v0
	v_mov_b32_e32 v29, v0
	v_mov_b32_e32 v30, v0
	v_mov_b32_e32 v31, v0
	v_mov_b32_e32 v40, v0
	v_mov_b32_e32 v41, v0
	v_mov_b32_e32 v42, v0
	v_mov_b32_e32 v43, v0
	v_mov_b32_e32 v44, v0
	v_mov_b32_e32 v45, v0
	v_mov_b32_e32 v46, v0
	v_mov_b32_e32 v47, v0
	v_mov_b32_e32 v56, v0
	v_mov_b32_e32 v57, v0
	v_mov_b32_e32 v58, v0
	v_mov_b32_e32 v59, v0
	v_mov_b32_e32 v60, v0
	v_mov_b32_e32 v61, v0
	v_mov_b32_e32 v62, v0
	v_mov_b32_e32 v63, v0
	v_mov_b32_e32 v64, v0
	v_mov_b32_e32 v65, v0
	v_mov_b32_e32 v66, v0
	v_mov_b32_e32 v67, v0
	v_mov_b32_e32 v68, v0
	v_mov_b32_e32 v69, v0
	v_mov_b32_e32 v70, v0
	v_mov_b32_e32 v71, v0
	v_mov_b32_e32 v80, v0
	v_mov_b32_e32 v81, v0
	v_mov_b32_e32 v82, v0
	v_mov_b32_e32 v83, v0
	v_mov_b32_e32 v84, v0
	v_mov_b32_e32 v85, v0
	v_mov_b32_e32 v86, v0
	v_mov_b32_e32 v87, v0
	v_mov_b32_e32 v96, v0
	v_mov_b32_e32 v97, v0
	v_mov_b32_e32 v98, v0
	v_mov_b32_e32 v99, v0
	v_mov_b32_e32 v100, v0
	v_mov_b32_e32 v101, v0
	v_mov_b32_e32 v102, v0
	v_mov_b32_e32 v103, v0
	v_mov_b32_e32 v116, v0
	v_mov_b32_e32 v117, v0
	v_mov_b32_e32 v118, v0
	v_mov_b32_e32 v119, v0
	v_mov_b32_e32 v112, v0
	v_mov_b32_e32 v113, v0
	v_mov_b32_e32 v114, v0
	v_mov_b32_e32 v115, v0
	v_mov_b32_e32 v72, v0
	v_mov_b32_e32 v73, v0
	v_mov_b32_e32 v74, v0
	v_mov_b32_e32 v75, v0
	v_mov_b32_e32 v76, v0
	v_mov_b32_e32 v77, v0
	v_mov_b32_e32 v78, v0
	v_mov_b32_e32 v79, v0
	v_mov_b32_e32 v88, v0
	v_mov_b32_e32 v89, v0
	v_mov_b32_e32 v90, v0
	v_mov_b32_e32 v91, v0
	v_mov_b32_e32 v92, v0
	v_mov_b32_e32 v93, v0
	v_mov_b32_e32 v94, v0
	v_mov_b32_e32 v95, v0
	v_mov_b32_e32 v104, v0
	v_mov_b32_e32 v105, v0
	v_mov_b32_e32 v106, v0
	v_mov_b32_e32 v107, v0
	v_mov_b32_e32 v108, v0
	v_mov_b32_e32 v109, v0
	v_mov_b32_e32 v110, v0
	v_mov_b32_e32 v111, v0
	v_mov_b32_e32 v120, v0
	v_mov_b32_e32 v121, v0
	v_mov_b32_e32 v122, v0
	v_mov_b32_e32 v123, v0
	v_mov_b32_e32 v124, v0
	v_mov_b32_e32 v125, v0
	v_mov_b32_e32 v126, v0
	v_mov_b32_e32 v127, v0
	.p2alignl 6, 3212836864

;     __device__ __forceinline__ size_t aoff(const Unit& u, size_t ts, int) const { return (size_t)u.pm * ts; }
;     __device__ __forceinline__ size_t boff(const Unit& u, size_t ts, int) const { return (size_t)u.pn * ts; }
;     __device__ __forceinline__ size_t aoff(const Unit& u, size_t ts, int K) const { return (size_t)(u.pm & 15) * ts + (size_t)(u.pm >> 4) * K * 2; }
;     __device__ __forceinline__ size_t boff(const Unit& u, size_t ts, int K) const { return (size_t)u.pn * ts + (size_t)(u.pm >> 4) * K * 2; }
; template <class Epi, class Sched, bool ALIGN_EPI = false, bool SP2 = false>
; __device__ __forceinline__ void gemm_phase(PG8_LAS unsigned char* lds, const Gemm g, const Sched& S, const Epi& E) {
;     ...
;         const bool has_next = S.next(ui + 1, nxt);
;         const char* nA = has_next ? (const char*)g.A + S.aoff(nxt, tstepA, K) : cA; const char* nB = has_next ? (const char*)g.Bt + S.boff(nxt, tstepB, K) : cB;
;     ...
; #pragma unroll
;         for (int a = 0; a < 2; ++a)
; #pragma unroll
;             for (int b = 0; b < 2; ++b)
; #pragma unroll
;                 for (int m = 0; m < 4; ++m)
; #pragma unroll
;                     for (int n = 0; n < 2; ++n) acc[a][b][m][n] = (f32x4){0.f, 0.f, 0.f, 0.f};
.LBB0_500:
	s_ashr_i32 s91, s90, 31
	s_lshl_b64 s[16:17], s[90:91], 18
	v_readlane_b32 s4, v252, 34
	v_readlane_b32 s5, v252, 35
	s_add_u32 s92, s4, s16
	s_addc_u32 s93, s5, s17
	s_ashr_i32 s89, s88, 31
	s_lshl_b64 s[16:17], s[88:89], 17
	v_readlane_b32 s4, v251, 50
	v_readlane_b32 s5, v251, 51
	s_add_u32 s94, s4, s16
	v_mov_b32_e32 v123, 0
	s_addc_u32 s95, s5, s17
	s_andn2_b64 vcc, exec, s[84:85]
	v_mov_b32_e32 v122, v123
	v_mov_b32_e32 v121, v123
	v_mov_b32_e32 v120, v123
	v_mov_b32_e32 v127, v123
	v_mov_b32_e32 v126, v123
	v_mov_b32_e32 v125, v123
	v_mov_b32_e32 v124, v123
	v_mov_b32_e32 v111, v123
	v_mov_b32_e32 v110, v123
	v_mov_b32_e32 v109, v123
	v_mov_b32_e32 v108, v123
	v_mov_b32_e32 v107, v123
	v_mov_b32_e32 v106, v123
	v_mov_b32_e32 v105, v123
	v_mov_b32_e32 v104, v123
	v_mov_b32_e32 v95, v123
	v_mov_b32_e32 v94, v123
	v_mov_b32_e32 v93, v123
	v_mov_b32_e32 v92, v123
	v_mov_b32_e32 v91, v123
	v_mov_b32_e32 v90, v123
	v_mov_b32_e32 v89, v123
	v_mov_b32_e32 v88, v123
	v_mov_b32_e32 v79, v123
	v_mov_b32_e32 v78, v123
	v_mov_b32_e32 v77, v123
	v_mov_b32_e32 v76, v123
	v_mov_b32_e32 v75, v123
	v_mov_b32_e32 v74, v123
	v_mov_b32_e32 v73, v123
	v_mov_b32_e32 v72, v123
	v_mov_b32_e32 v119, v123
	v_mov_b32_e32 v118, v123
	v_mov_b32_e32 v117, v123
	v_mov_b32_e32 v116, v123
	v_mov_b32_e32 v115, v123
	v_mov_b32_e32 v114, v123
	v_mov_b32_e32 v113, v123
	v_mov_b32_e32 v112, v123
	v_mov_b32_e32 v103, v123
	v_mov_b32_e32 v102, v123
	v_mov_b32_e32 v101, v123
	v_mov_b32_e32 v100, v123
	v_mov_b32_e32 v99, v123
	v_mov_b32_e32 v98, v123
	v_mov_b32_e32 v97, v123
	v_mov_b32_e32 v96, v123
	v_mov_b32_e32 v87, v123
	v_mov_b32_e32 v86, v123
	v_mov_b32_e32 v85, v123
	v_mov_b32_e32 v84, v123
	v_mov_b32_e32 v83, v123
	v_mov_b32_e32 v82, v123
	v_mov_b32_e32 v81, v123
	v_mov_b32_e32 v80, v123
	v_mov_b32_e32 v71, v123
	v_mov_b32_e32 v70, v123
	v_mov_b32_e32 v69, v123
	v_mov_b32_e32 v68, v123
	v_mov_b32_e32 v67, v123
	v_mov_b32_e32 v66, v123
	v_mov_b32_e32 v65, v123
	v_mov_b32_e32 v64, v123
	v_mov_b32_e32 v63, v123
	v_mov_b32_e32 v62, v123
	v_mov_b32_e32 v61, v123
	v_mov_b32_e32 v60, v123
	v_mov_b32_e32 v59, v123
	v_mov_b32_e32 v58, v123
	v_mov_b32_e32 v57, v123
	v_mov_b32_e32 v56, v123
	v_mov_b32_e32 v47, v123
	v_mov_b32_e32 v46, v123
	v_mov_b32_e32 v45, v123
	v_mov_b32_e32 v44, v123
	v_mov_b32_e32 v43, v123
	v_mov_b32_e32 v42, v123
	v_mov_b32_e32 v41, v123
	v_mov_b32_e32 v40, v123
	v_mov_b32_e32 v31, v123
	v_mov_b32_e32 v30, v123
	v_mov_b32_e32 v29, v123
	v_mov_b32_e32 v28, v123
	v_mov_b32_e32 v27, v123
	v_mov_b32_e32 v26, v123
	v_mov_b32_e32 v25, v123
	v_mov_b32_e32 v24, v123
	s_waitcnt lgkmcnt(0)
	v_mov_b32_e32 v15, v123
	v_mov_b32_e32 v14, v123
	v_mov_b32_e32 v13, v123
	v_mov_b32_e32 v12, v123
	v_mov_b32_e32 v11, v123
	v_mov_b32_e32 v10, v123
	v_mov_b32_e32 v9, v123
	v_mov_b32_e32 v8, v123
	v_mov_b32_e32 v55, v123
	v_mov_b32_e32 v54, v123
	v_mov_b32_e32 v53, v123
	v_mov_b32_e32 v52, v123
	v_mov_b32_e32 v51, v123
	v_mov_b32_e32 v50, v123
	v_mov_b32_e32 v49, v123
	v_mov_b32_e32 v48, v123
	v_mov_b32_e32 v39, v123
	v_mov_b32_e32 v38, v123
	v_mov_b32_e32 v37, v123
	v_mov_b32_e32 v36, v123
	v_mov_b32_e32 v35, v123
	v_mov_b32_e32 v34, v123
	v_mov_b32_e32 v33, v123
	v_mov_b32_e32 v32, v123
	v_mov_b32_e32 v23, v123
	v_mov_b32_e32 v22, v123
	v_mov_b32_e32 v21, v123
	v_mov_b32_e32 v20, v123
	v_mov_b32_e32 v19, v123
	v_mov_b32_e32 v18, v123
	v_mov_b32_e32 v17, v123
	v_mov_b32_e32 v16, v123
	v_mov_b32_e32 v7, v123
	v_mov_b32_e32 v6, v123
	v_mov_b32_e32 v5, v123
	v_mov_b32_e32 v4, v123
	v_mov_b32_e32 v3, v123
	v_mov_b32_e32 v2, v123
	v_mov_b32_e32 v1, v123
	v_mov_b32_e32 v0, v123
	s_cbranch_vccnz .LBB0_503
	s_and_b64 s[16:17], s[38:39], exec
	s_cselect_b32 s15, s93, s43
	s_cselect_b32 s16, s92, s42
	s_cselect_b32 s17, s95, s45
	s_cselect_b32 s33, s94, s44
	s_add_u32 s42, s42, 0x20080
	s_addc_u32 s43, s43, 0
	s_add_u32 s35, s44, 0x100
	v_mov_b32_e32 v0, 0
	s_addc_u32 s41, s45, 0
	s_mov_b32 s44, 0
	v_mov_b32_e32 v1, v0
	v_mov_b32_e32 v2, v0
	v_mov_b32_e32 v3, v0
	v_mov_b32_e32 v4, v0
	v_mov_b32_e32 v5, v0
	v_mov_b32_e32 v6, v0
	v_mov_b32_e32 v7, v0
	v_mov_b32_e32 v16, v0
	v_mov_b32_e32 v17, v0
	v_mov_b32_e32 v18, v0
	v_mov_b32_e32 v19, v0
	v_mov_b32_e32 v20, v0
	v_mov_b32_e32 v21, v0
	v_mov_b32_e32 v22, v0
	v_mov_b32_e32 v23, v0
	v_mov_b32_e32 v32, v0
	v_mov_b32_e32 v33, v0
	v_mov_b32_e32 v34, v0
	v_mov_b32_e32 v35, v0
	v_mov_b32_e32 v36, v0
	v_mov_b32_e32 v37, v0
	v_mov_b32_e32 v38, v0
	v_mov_b32_e32 v39, v0
	v_mov_b32_e32 v48, v0
	v_mov_b32_e32 v49, v0
	v_mov_b32_e32 v50, v0
	v_mov_b32_e32 v51, v0
	v_mov_b32_e32 v52, v0
	v_mov_b32_e32 v53, v0
	v_mov_b32_e32 v54, v0
	v_mov_b32_e32 v55, v0
	v_mov_b32_e32 v8, v0
	v_mov_b32_e32 v9, v0
	v_mov_b32_e32 v10, v0
	v_mov_b32_e32 v11, v0
	v_mov_b32_e32 v12, v0
	v_mov_b32_e32 v13, v0
	v_mov_b32_e32 v14, v0
	v_mov_b32_e32 v15, v0
	v_mov_b32_e32 v24, v0
	v_mov_b32_e32 v25, v0
	v_mov_b32_e32 v26, v0
	v_mov_b32_e32 v27, v0
	v_mov_b32_e32 v28, v0
	v_mov_b32_e32 v29, v0
	v_mov_b32_e32 v30, v0
	v_mov_b32_e32 v31, v0
	v_mov_b32_e32 v40, v0
	v_mov_b32_e32 v41, v0
	v_mov_b32_e32 v42, v0
	v_mov_b32_e32 v43, v0
	v_mov_b32_e32 v44, v0
	v_mov_b32_e32 v45, v0
	v_mov_b32_e32 v46, v0
	v_mov_b32_e32 v47, v0
	v_mov_b32_e32 v56, v0
	v_mov_b32_e32 v57, v0
	v_mov_b32_e32 v58, v0
	v_mov_b32_e32 v59, v0
	v_mov_b32_e32 v60, v0
	v_mov_b32_e32 v61, v0
	v_mov_b32_e32 v62, v0
	v_mov_b32_e32 v63, v0
	v_mov_b32_e32 v64, v0
	v_mov_b32_e32 v65, v0
	v_mov_b32_e32 v66, v0
	v_mov_b32_e32 v67, v0
	v_mov_b32_e32 v68, v0
	v_mov_b32_e32 v69, v0
	v_mov_b32_e32 v70, v0
	v_mov_b32_e32 v71, v0
	v_mov_b32_e32 v80, v0
	v_mov_b32_e32 v81, v0
	v_mov_b32_e32 v82, v0
	v_mov_b32_e32 v83, v0
	v_mov_b32_e32 v84, v0
	v_mov_b32_e32 v85, v0
	v_mov_b32_e32 v86, v0
	v_mov_b32_e32 v87, v0
	v_mov_b32_e32 v96, v0
	v_mov_b32_e32 v97, v0
	v_mov_b32_e32 v98, v0
	v_mov_b32_e32 v99, v0
	v_mov_b32_e32 v100, v0
	v_mov_b32_e32 v101, v0
	v_mov_b32_e32 v102, v0
	v_mov_b32_e32 v103, v0
	v_mov_b32_e32 v112, v0
	v_mov_b32_e32 v113, v0
	v_mov_b32_e32 v114, v0
	v_mov_b32_e32 v115, v0
	v_mov_b32_e32 v116, v0
	v_mov_b32_e32 v117, v0
	v_mov_b32_e32 v118, v0
	v_mov_b32_e32 v119, v0
	v_mov_b32_e32 v72, v0
	v_mov_b32_e32 v73, v0
	v_mov_b32_e32 v74, v0
	v_mov_b32_e32 v75, v0
	v_mov_b32_e32 v76, v0
	v_mov_b32_e32 v77, v0
	v_mov_b32_e32 v78, v0
	v_mov_b32_e32 v79, v0
	v_mov_b32_e32 v88, v0
	v_mov_b32_e32 v89, v0
	v_mov_b32_e32 v90, v0
	v_mov_b32_e32 v91, v0
	v_mov_b32_e32 v92, v0
	v_mov_b32_e32 v93, v0
	v_mov_b32_e32 v94, v0
	v_mov_b32_e32 v95, v0
	v_mov_b32_e32 v104, v0
	v_mov_b32_e32 v105, v0
	v_mov_b32_e32 v106, v0
	v_mov_b32_e32 v107, v0
	v_mov_b32_e32 v108, v0
	v_mov_b32_e32 v109, v0
	v_mov_b32_e32 v110, v0
	v_mov_b32_e32 v111, v0
	v_mov_b32_e32 v124, v0
	v_mov_b32_e32 v125, v0
	v_mov_b32_e32 v126, v0
	v_mov_b32_e32 v127, v0
	v_mov_b32_e32 v120, v0
	v_mov_b32_e32 v121, v0
	v_mov_b32_e32 v122, v0
	v_mov_b32_e32 v123, v0
	.p2alignl 6, 3212836864

;     __device__ __forceinline__ size_t aoff(const Unit& u, size_t ts, int) const { return (size_t)u.pm * ts; }
;     __device__ __forceinline__ size_t boff(const Unit& u, size_t ts, int) const { return (size_t)u.pn * ts; }
;     __device__ __forceinline__ size_t aoff(const Unit& u, size_t ts, int K) const { return (size_t)(u.pm & 15) * ts + (size_t)(u.pm >> 4) * K * 2; }
;     __device__ __forceinline__ size_t boff(const Unit& u, size_t ts, int K) const { return (size_t)u.pn * ts + (size_t)(u.pm >> 4) * K * 2; }
; template <class Epi, class Sched, bool ALIGN_EPI = false, bool SP2 = false>
; __device__ __forceinline__ void gemm_phase(PG8_LAS unsigned char* lds, const Gemm g, const Sched& S, const Epi& E) {
;     ...
;         const bool has_next = S.next(ui + 1, nxt);
;         const char* nA = has_next ? (const char*)g.A + S.aoff(nxt, tstepA, K) : cA; const char* nB = has_next ? (const char*)g.Bt + S.boff(nxt, tstepB, K) : cB;
;     ...
; #pragma unroll
;         for (int a = 0; a < 2; ++a)
; #pragma unroll
;             for (int b = 0; b < 2; ++b)
; #pragma unroll
;                 for (int m = 0; m < 4; ++m)
; #pragma unroll
;                     for (int n = 0; n < 2; ++n) acc[a][b][m][n] = (f32x4){0.f, 0.f, 0.f, 0.f};
.LBB0_567:
	s_ashr_i32 s53, s52, 31
	s_lshl_b64 s[28:29], s[52:53], 18
	v_readlane_b32 s4, v253, 60
	s_add_u32 s68, s4, s28
	v_readlane_b32 s4, v253, 61
	s_addc_u32 s69, s4, s29
	s_ashr_i32 s49, s48, 31
	s_lshl_b64 s[28:29], s[48:49], 16
	v_readlane_b32 s4, v251, 52
	v_readlane_b32 s5, v251, 53
	s_add_u32 s76, s4, s28
	v_mov_b32_e32 v127, 0
	s_addc_u32 s77, s5, s29
	s_andn2_b64 vcc, exec, s[40:41]
	v_mov_b32_e32 v126, v127
	v_mov_b32_e32 v125, v127
	v_mov_b32_e32 v124, v127
	v_mov_b32_e32 v123, v127
	v_mov_b32_e32 v122, v127
	v_mov_b32_e32 v121, v127
	v_mov_b32_e32 v120, v127
	v_mov_b32_e32 v111, v127
	v_mov_b32_e32 v110, v127
	v_mov_b32_e32 v109, v127
	v_mov_b32_e32 v108, v127
	v_mov_b32_e32 v107, v127
	v_mov_b32_e32 v106, v127
	v_mov_b32_e32 v105, v127
	v_mov_b32_e32 v104, v127
	v_mov_b32_e32 v95, v127
	v_mov_b32_e32 v94, v127
	v_mov_b32_e32 v93, v127
	v_mov_b32_e32 v92, v127
	v_mov_b32_e32 v91, v127
	v_mov_b32_e32 v90, v127
	v_mov_b32_e32 v89, v127
	v_mov_b32_e32 v88, v127
	v_mov_b32_e32 v79, v127
	v_mov_b32_e32 v78, v127
	v_mov_b32_e32 v77, v127
	v_mov_b32_e32 v76, v127
	v_mov_b32_e32 v75, v127
	v_mov_b32_e32 v74, v127
	v_mov_b32_e32 v73, v127
	v_mov_b32_e32 v72, v127
	v_mov_b32_e32 v119, v127
	v_mov_b32_e32 v118, v127
	v_mov_b32_e32 v117, v127
	v_mov_b32_e32 v116, v127
	v_mov_b32_e32 v115, v127
	v_mov_b32_e32 v114, v127
	v_mov_b32_e32 v113, v127
	v_mov_b32_e32 v112, v127
	v_mov_b32_e32 v103, v127
	v_mov_b32_e32 v102, v127
	v_mov_b32_e32 v101, v127
	v_mov_b32_e32 v100, v127
	v_mov_b32_e32 v99, v127
	v_mov_b32_e32 v98, v127
	v_mov_b32_e32 v97, v127
	v_mov_b32_e32 v96, v127
	v_mov_b32_e32 v87, v127
	v_mov_b32_e32 v86, v127
	v_mov_b32_e32 v85, v127
	v_mov_b32_e32 v84, v127
	v_mov_b32_e32 v83, v127
	v_mov_b32_e32 v82, v127
	v_mov_b32_e32 v81, v127
	v_mov_b32_e32 v80, v127
	v_mov_b32_e32 v71, v127
	v_mov_b32_e32 v70, v127
	v_mov_b32_e32 v69, v127
	v_mov_b32_e32 v68, v127
	v_mov_b32_e32 v67, v127
	v_mov_b32_e32 v66, v127
	v_mov_b32_e32 v65, v127
	v_mov_b32_e32 v64, v127
	v_mov_b32_e32 v63, v127
	v_mov_b32_e32 v62, v127
	v_mov_b32_e32 v61, v127
	v_mov_b32_e32 v60, v127
	v_mov_b32_e32 v59, v127
	v_mov_b32_e32 v58, v127
	v_mov_b32_e32 v57, v127
	v_mov_b32_e32 v56, v127
	v_mov_b32_e32 v47, v127
	v_mov_b32_e32 v46, v127
	v_mov_b32_e32 v45, v127
	v_mov_b32_e32 v44, v127
	v_mov_b32_e32 v43, v127
	v_mov_b32_e32 v42, v127
	v_mov_b32_e32 v41, v127
	v_mov_b32_e32 v40, v127
	v_mov_b32_e32 v31, v127
	v_mov_b32_e32 v30, v127
	v_mov_b32_e32 v29, v127
	v_mov_b32_e32 v28, v127
	v_mov_b32_e32 v27, v127
	v_mov_b32_e32 v26, v127
	v_mov_b32_e32 v25, v127
	v_mov_b32_e32 v24, v127
	v_mov_b32_e32 v15, v127
	v_mov_b32_e32 v14, v127
	v_mov_b32_e32 v13, v127
	v_mov_b32_e32 v12, v127
	v_mov_b32_e32 v11, v127
	v_mov_b32_e32 v10, v127
	v_mov_b32_e32 v9, v127
	v_mov_b32_e32 v8, v127
	v_mov_b32_e32 v55, v127
	v_mov_b32_e32 v54, v127
	v_mov_b32_e32 v53, v127
	v_mov_b32_e32 v52, v127
	v_mov_b32_e32 v51, v127
	v_mov_b32_e32 v50, v127
	v_mov_b32_e32 v49, v127
	v_mov_b32_e32 v48, v127
	v_mov_b32_e32 v39, v127
	v_mov_b32_e32 v38, v127
	v_mov_b32_e32 v37, v127
	v_mov_b32_e32 v36, v127
	v_mov_b32_e32 v35, v127
	v_mov_b32_e32 v34, v127
	v_mov_b32_e32 v33, v127
	v_mov_b32_e32 v32, v127
	v_mov_b32_e32 v23, v127
	v_mov_b32_e32 v22, v127
	v_mov_b32_e32 v21, v127
	v_mov_b32_e32 v20, v127
	v_mov_b32_e32 v19, v127
	v_mov_b32_e32 v18, v127
	v_mov_b32_e32 v17, v127
	v_mov_b32_e32 v16, v127
	v_mov_b32_e32 v7, v127
	v_mov_b32_e32 v6, v127
	v_mov_b32_e32 v5, v127
	v_mov_b32_e32 v4, v127
	v_mov_b32_e32 v3, v127
	v_mov_b32_e32 v2, v127
	v_mov_b32_e32 v1, v127
	v_mov_b32_e32 v0, v127
	s_cbranch_vccnz .LBB0_570
	s_and_b64 s[28:29], s[38:39], exec
	s_cselect_b32 s28, s69, s85
	s_cselect_b32 s29, s68, s84
	s_cselect_b32 s33, s77, s87
	s_cselect_b32 s47, s76, s86
	s_add_u32 s84, s84, 0x20080
	s_addc_u32 s85, s85, 0
	s_add_u32 s49, s86, 0x100
	v_mov_b32_e32 v0, 0
	s_addc_u32 s53, s87, 0
	s_mov_b32 s55, 0
	v_mov_b32_e32 v1, v0
	v_mov_b32_e32 v2, v0
	v_mov_b32_e32 v3, v0
	v_mov_b32_e32 v4, v0
	v_mov_b32_e32 v5, v0
	v_mov_b32_e32 v6, v0
	v_mov_b32_e32 v7, v0
	v_mov_b32_e32 v16, v0
	v_mov_b32_e32 v17, v0
	v_mov_b32_e32 v18, v0
	v_mov_b32_e32 v19, v0
	v_mov_b32_e32 v20, v0
	v_mov_b32_e32 v21, v0
	v_mov_b32_e32 v22, v0
	v_mov_b32_e32 v23, v0
	v_mov_b32_e32 v32, v0
	v_mov_b32_e32 v33, v0
	v_mov_b32_e32 v34, v0
	v_mov_b32_e32 v35, v0
	v_mov_b32_e32 v36, v0
	v_mov_b32_e32 v37, v0
	v_mov_b32_e32 v38, v0
	v_mov_b32_e32 v39, v0
	v_mov_b32_e32 v48, v0
	v_mov_b32_e32 v49, v0
	v_mov_b32_e32 v50, v0
	v_mov_b32_e32 v51, v0
	v_mov_b32_e32 v52, v0
	v_mov_b32_e32 v53, v0
	v_mov_b32_e32 v54, v0
	v_mov_b32_e32 v55, v0
	v_mov_b32_e32 v8, v0
	v_mov_b32_e32 v9, v0
	v_mov_b32_e32 v10, v0
	v_mov_b32_e32 v11, v0
	v_mov_b32_e32 v12, v0
	v_mov_b32_e32 v13, v0
	v_mov_b32_e32 v14, v0
	v_mov_b32_e32 v15, v0
	v_mov_b32_e32 v24, v0
	v_mov_b32_e32 v25, v0
	v_mov_b32_e32 v26, v0
	v_mov_b32_e32 v27, v0
	v_mov_b32_e32 v28, v0
	v_mov_b32_e32 v29, v0
	v_mov_b32_e32 v30, v0
	v_mov_b32_e32 v31, v0
	v_mov_b32_e32 v40, v0
	v_mov_b32_e32 v41, v0
	v_mov_b32_e32 v42, v0
	v_mov_b32_e32 v43, v0
	v_mov_b32_e32 v44, v0
	v_mov_b32_e32 v45, v0
	v_mov_b32_e32 v46, v0
	v_mov_b32_e32 v47, v0
	v_mov_b32_e32 v56, v0
	v_mov_b32_e32 v57, v0
	v_mov_b32_e32 v58, v0
	v_mov_b32_e32 v59, v0
	v_mov_b32_e32 v60, v0
	v_mov_b32_e32 v61, v0
	v_mov_b32_e32 v62, v0
	v_mov_b32_e32 v63, v0
	v_mov_b32_e32 v64, v0
	v_mov_b32_e32 v65, v0
	v_mov_b32_e32 v66, v0
	v_mov_b32_e32 v67, v0
	v_mov_b32_e32 v68, v0
	v_mov_b32_e32 v69, v0
	v_mov_b32_e32 v70, v0
	v_mov_b32_e32 v71, v0
	v_mov_b32_e32 v80, v0
	v_mov_b32_e32 v81, v0
	v_mov_b32_e32 v82, v0
	v_mov_b32_e32 v83, v0
	v_mov_b32_e32 v84, v0
	v_mov_b32_e32 v85, v0
	v_mov_b32_e32 v86, v0
	v_mov_b32_e32 v87, v0
	v_mov_b32_e32 v96, v0
	v_mov_b32_e32 v97, v0
	v_mov_b32_e32 v98, v0
	v_mov_b32_e32 v99, v0
	v_mov_b32_e32 v100, v0
	v_mov_b32_e32 v101, v0
	v_mov_b32_e32 v102, v0
	v_mov_b32_e32 v103, v0
	v_mov_b32_e32 v112, v0
	v_mov_b32_e32 v113, v0
	v_mov_b32_e32 v114, v0
	v_mov_b32_e32 v115, v0
	v_mov_b32_e32 v116, v0
	v_mov_b32_e32 v117, v0
	v_mov_b32_e32 v118, v0
	v_mov_b32_e32 v119, v0
	v_mov_b32_e32 v72, v0
	v_mov_b32_e32 v73, v0
	v_mov_b32_e32 v74, v0
	v_mov_b32_e32 v75, v0
	v_mov_b32_e32 v76, v0
	v_mov_b32_e32 v77, v0
	v_mov_b32_e32 v78, v0
	v_mov_b32_e32 v79, v0
	v_mov_b32_e32 v88, v0
	v_mov_b32_e32 v89, v0
	v_mov_b32_e32 v90, v0
	v_mov_b32_e32 v91, v0
	v_mov_b32_e32 v92, v0
	v_mov_b32_e32 v93, v0
	v_mov_b32_e32 v94, v0
	v_mov_b32_e32 v95, v0
	v_mov_b32_e32 v104, v0
	v_mov_b32_e32 v105, v0
	v_mov_b32_e32 v106, v0
	v_mov_b32_e32 v107, v0
	v_mov_b32_e32 v108, v0
	v_mov_b32_e32 v109, v0
	v_mov_b32_e32 v110, v0
	v_mov_b32_e32 v111, v0
	v_mov_b32_e32 v120, v0
	v_mov_b32_e32 v121, v0
	v_mov_b32_e32 v122, v0
	v_mov_b32_e32 v123, v0
	v_mov_b32_e32 v124, v0
	v_mov_b32_e32 v125, v0
	v_mov_b32_e32 v126, v0
	v_mov_b32_e32 v127, v0
	.p2alignl 6, 3212836864

;     __device__ __forceinline__ size_t aoff(const Unit& u, size_t ts, int) const { return (size_t)u.pm * ts; }
;     __device__ __forceinline__ size_t boff(const Unit& u, size_t ts, int) const { return (size_t)u.pn * ts; }
;     __device__ __forceinline__ size_t aoff(const Unit& u, size_t ts, int K) const { return (size_t)(u.pm & 15) * ts + (size_t)(u.pm >> 4) * K * 2; }
;     __device__ __forceinline__ size_t boff(const Unit& u, size_t ts, int K) const { return (size_t)u.pn * ts + (size_t)(u.pm >> 4) * K * 2; }
; template <class Epi, class Sched, bool ALIGN_EPI = false, bool SP2 = false>
; __device__ __forceinline__ void gemm_phase(PG8_LAS unsigned char* lds, const Gemm g, const Sched& S, const Epi& E) {
;     ...
;         const bool has_next = S.next(ui + 1, nxt);
;         const char* nA = has_next ? (const char*)g.A + S.aoff(nxt, tstepA, K) : cA; const char* nB = has_next ? (const char*)g.Bt + S.boff(nxt, tstepB, K) : cB;
;     ...
; #pragma unroll
;         for (int a = 0; a < 2; ++a)
; #pragma unroll
;             for (int b = 0; b < 2; ++b)
; #pragma unroll
;                 for (int m = 0; m < 4; ++m)
; #pragma unroll
;                     for (int n = 0; n < 2; ++n) acc[a][b][m][n] = (f32x4){0.f, 0.f, 0.f, 0.f};
.LBB0_616:
	s_ashr_i32 s69, s68, 31
	s_lshl_b64 s[62:63], s[68:69], 16
	v_readlane_b32 s4, v253, 62
	s_add_u32 s76, s4, s62
	v_readlane_b32 s4, v253, 63
	s_addc_u32 s77, s4, s63
	s_ashr_i32 s53, s52, 31
	s_lshl_b64 s[62:63], s[52:53], 18
	v_readlane_b32 s4, v253, 60
	s_add_u32 s80, s4, s62
	v_readlane_b32 s4, v253, 61
	v_mov_b32_e32 v127, 0
	s_addc_u32 s81, s4, s63
	s_andn2_b64 vcc, exec, s[46:47]
	v_mov_b32_e32 v126, v127
	v_mov_b32_e32 v125, v127
	v_mov_b32_e32 v124, v127
	v_mov_b32_e32 v123, v127
	v_mov_b32_e32 v122, v127
	v_mov_b32_e32 v121, v127
	v_mov_b32_e32 v120, v127
	v_mov_b32_e32 v119, v127
	v_mov_b32_e32 v118, v127
	v_mov_b32_e32 v117, v127
	v_mov_b32_e32 v116, v127
	v_mov_b32_e32 v115, v127
	v_mov_b32_e32 v114, v127
	v_mov_b32_e32 v113, v127
	v_mov_b32_e32 v112, v127
	v_mov_b32_e32 v111, v127
	v_mov_b32_e32 v110, v127
	v_mov_b32_e32 v109, v127
	v_mov_b32_e32 v108, v127
	v_mov_b32_e32 v107, v127
	v_mov_b32_e32 v106, v127
	v_mov_b32_e32 v105, v127
	v_mov_b32_e32 v104, v127
	v_mov_b32_e32 v103, v127
	v_mov_b32_e32 v102, v127
	v_mov_b32_e32 v101, v127
	v_mov_b32_e32 v100, v127
	v_mov_b32_e32 v99, v127
	v_mov_b32_e32 v98, v127
	v_mov_b32_e32 v97, v127
	v_mov_b32_e32 v96, v127
	v_mov_b32_e32 v63, v127
	v_mov_b32_e32 v62, v127
	v_mov_b32_e32 v61, v127
	v_mov_b32_e32 v60, v127
	v_mov_b32_e32 v59, v127
	v_mov_b32_e32 v58, v127
	v_mov_b32_e32 v57, v127
	v_mov_b32_e32 v56, v127
	v_mov_b32_e32 v55, v127
	v_mov_b32_e32 v54, v127
	v_mov_b32_e32 v53, v127
	v_mov_b32_e32 v52, v127
	v_mov_b32_e32 v51, v127
	v_mov_b32_e32 v50, v127
	v_mov_b32_e32 v49, v127
	v_mov_b32_e32 v48, v127
	v_mov_b32_e32 v47, v127
	v_mov_b32_e32 v46, v127
	v_mov_b32_e32 v45, v127
	v_mov_b32_e32 v44, v127
	v_mov_b32_e32 v43, v127
	v_mov_b32_e32 v42, v127
	v_mov_b32_e32 v41, v127
	v_mov_b32_e32 v40, v127
	v_mov_b32_e32 v39, v127
	v_mov_b32_e32 v38, v127
	v_mov_b32_e32 v37, v127
	v_mov_b32_e32 v36, v127
	v_mov_b32_e32 v35, v127
	v_mov_b32_e32 v34, v127
	v_mov_b32_e32 v33, v127
	v_mov_b32_e32 v32, v127
	v_mov_b32_e32 v95, v127
	v_mov_b32_e32 v94, v127
	v_mov_b32_e32 v93, v127
	v_mov_b32_e32 v92, v127
	v_mov_b32_e32 v91, v127
	v_mov_b32_e32 v90, v127
	v_mov_b32_e32 v89, v127
	v_mov_b32_e32 v88, v127
	v_mov_b32_e32 v87, v127
	v_mov_b32_e32 v86, v127
	v_mov_b32_e32 v85, v127
	v_mov_b32_e32 v84, v127
	v_mov_b32_e32 v83, v127
	v_mov_b32_e32 v82, v127
	v_mov_b32_e32 v81, v127
	v_mov_b32_e32 v80, v127
	v_mov_b32_e32 v79, v127
	v_mov_b32_e32 v78, v127
	v_mov_b32_e32 v77, v127
	v_mov_b32_e32 v76, v127
	v_mov_b32_e32 v75, v127
	v_mov_b32_e32 v74, v127
	v_mov_b32_e32 v73, v127
	v_mov_b32_e32 v72, v127
	v_mov_b32_e32 v71, v127
	v_mov_b32_e32 v70, v127
	v_mov_b32_e32 v69, v127
	v_mov_b32_e32 v68, v127
	v_mov_b32_e32 v67, v127
	v_mov_b32_e32 v66, v127
	v_mov_b32_e32 v65, v127
	v_mov_b32_e32 v64, v127
	v_mov_b32_e32 v31, v127
	v_mov_b32_e32 v30, v127
	v_mov_b32_e32 v29, v127
	v_mov_b32_e32 v28, v127
	v_mov_b32_e32 v27, v127
	v_mov_b32_e32 v26, v127
	v_mov_b32_e32 v25, v127
	v_mov_b32_e32 v24, v127
	v_mov_b32_e32 v23, v127
	v_mov_b32_e32 v22, v127
	v_mov_b32_e32 v21, v127
	v_mov_b32_e32 v20, v127
	v_mov_b32_e32 v19, v127
	v_mov_b32_e32 v18, v127
	v_mov_b32_e32 v17, v127
	v_mov_b32_e32 v16, v127
	v_mov_b32_e32 v15, v127
	v_mov_b32_e32 v14, v127
	v_mov_b32_e32 v13, v127
	v_mov_b32_e32 v12, v127
	v_mov_b32_e32 v11, v127
	v_mov_b32_e32 v10, v127
	v_mov_b32_e32 v9, v127
	v_mov_b32_e32 v8, v127
	v_mov_b32_e32 v7, v127
	v_mov_b32_e32 v6, v127
	v_mov_b32_e32 v5, v127
	v_mov_b32_e32 v4, v127
	v_mov_b32_e32 v3, v127
	v_mov_b32_e32 v2, v127
	v_mov_b32_e32 v1, v127
	v_mov_b32_e32 v0, v127
	s_cbranch_vccnz .LBB0_619
	s_and_b64 s[62:63], s[38:39], exec
	s_cselect_b32 s41, s77, s43
	s_cselect_b32 s53, s76, s42
	s_cselect_b32 s59, s81, s85
	s_cselect_b32 s64, s80, s84
	s_add_u32 s42, s42, 0x8080
	s_addc_u32 s43, s43, 0
	s_add_u32 s69, s84, 0x100
	v_mov_b32_e32 v0, 0
	s_addc_u32 s78, s85, 0
	s_mov_b32 s62, 0
	v_mov_b32_e32 v1, v0
	v_mov_b32_e32 v2, v0
	v_mov_b32_e32 v3, v0
	v_mov_b32_e32 v4, v0
	v_mov_b32_e32 v5, v0
	v_mov_b32_e32 v6, v0
	v_mov_b32_e32 v7, v0
	v_mov_b32_e32 v8, v0
	v_mov_b32_e32 v9, v0
	v_mov_b32_e32 v10, v0
	v_mov_b32_e32 v11, v0
	v_mov_b32_e32 v12, v0
	v_mov_b32_e32 v13, v0
	v_mov_b32_e32 v14, v0
	v_mov_b32_e32 v15, v0
	v_mov_b32_e32 v16, v0
	v_mov_b32_e32 v17, v0
	v_mov_b32_e32 v18, v0
	v_mov_b32_e32 v19, v0
	v_mov_b32_e32 v20, v0
	v_mov_b32_e32 v21, v0
	v_mov_b32_e32 v22, v0
	v_mov_b32_e32 v23, v0
	v_mov_b32_e32 v24, v0
	v_mov_b32_e32 v25, v0
	v_mov_b32_e32 v26, v0
	v_mov_b32_e32 v27, v0
	v_mov_b32_e32 v28, v0
	v_mov_b32_e32 v29, v0
	v_mov_b32_e32 v30, v0
	v_mov_b32_e32 v31, v0
	v_mov_b32_e32 v64, v0
	v_mov_b32_e32 v65, v0
	v_mov_b32_e32 v66, v0
	v_mov_b32_e32 v67, v0
	v_mov_b32_e32 v68, v0
	v_mov_b32_e32 v69, v0
	v_mov_b32_e32 v70, v0
	v_mov_b32_e32 v71, v0
	v_mov_b32_e32 v72, v0
	v_mov_b32_e32 v73, v0
	v_mov_b32_e32 v74, v0
	v_mov_b32_e32 v75, v0
	v_mov_b32_e32 v76, v0
	v_mov_b32_e32 v77, v0
	v_mov_b32_e32 v78, v0
	v_mov_b32_e32 v79, v0
	v_mov_b32_e32 v80, v0
	v_mov_b32_e32 v81, v0
	v_mov_b32_e32 v82, v0
	v_mov_b32_e32 v83, v0
	v_mov_b32_e32 v84, v0
	v_mov_b32_e32 v85, v0
	v_mov_b32_e32 v86, v0
	v_mov_b32_e32 v87, v0
	v_mov_b32_e32 v88, v0
	v_mov_b32_e32 v89, v0
	v_mov_b32_e32 v90, v0
	v_mov_b32_e32 v91, v0
	v_mov_b32_e32 v92, v0
	v_mov_b32_e32 v93, v0
	v_mov_b32_e32 v94, v0
	v_mov_b32_e32 v95, v0
	v_mov_b32_e32 v32, v0
	v_mov_b32_e32 v33, v0
	v_mov_b32_e32 v34, v0
	v_mov_b32_e32 v35, v0
	v_mov_b32_e32 v36, v0
	v_mov_b32_e32 v37, v0
	v_mov_b32_e32 v38, v0
	v_mov_b32_e32 v39, v0
	v_mov_b32_e32 v40, v0
	v_mov_b32_e32 v41, v0
	v_mov_b32_e32 v42, v0
	v_mov_b32_e32 v43, v0
	v_mov_b32_e32 v44, v0
	v_mov_b32_e32 v45, v0
	v_mov_b32_e32 v46, v0
	v_mov_b32_e32 v47, v0
	v_mov_b32_e32 v48, v0
	v_mov_b32_e32 v49, v0
	v_mov_b32_e32 v50, v0
	v_mov_b32_e32 v51, v0
	v_mov_b32_e32 v52, v0
	v_mov_b32_e32 v53, v0
	v_mov_b32_e32 v54, v0
	v_mov_b32_e32 v55, v0
	v_mov_b32_e32 v56, v0
	v_mov_b32_e32 v57, v0
	v_mov_b32_e32 v58, v0
	v_mov_b32_e32 v59, v0
	v_mov_b32_e32 v60, v0
	v_mov_b32_e32 v61, v0
	v_mov_b32_e32 v62, v0
	v_mov_b32_e32 v63, v0
	v_mov_b32_e32 v96, v0
	v_mov_b32_e32 v97, v0
	v_mov_b32_e32 v98, v0
	v_mov_b32_e32 v99, v0
	v_mov_b32_e32 v100, v0
	v_mov_b32_e32 v101, v0
	v_mov_b32_e32 v102, v0
	v_mov_b32_e32 v103, v0
	v_mov_b32_e32 v104, v0
	v_mov_b32_e32 v105, v0
	v_mov_b32_e32 v106, v0
	v_mov_b32_e32 v107, v0
	v_mov_b32_e32 v108, v0
	v_mov_b32_e32 v109, v0
	v_mov_b32_e32 v110, v0
	v_mov_b32_e32 v111, v0
	v_mov_b32_e32 v112, v0
	v_mov_b32_e32 v113, v0
	v_mov_b32_e32 v114, v0
	v_mov_b32_e32 v115, v0
	v_mov_b32_e32 v116, v0
	v_mov_b32_e32 v117, v0
	v_mov_b32_e32 v118, v0
	v_mov_b32_e32 v119, v0
	v_mov_b32_e32 v120, v0
	v_mov_b32_e32 v121, v0
	v_mov_b32_e32 v122, v0
	v_mov_b32_e32 v123, v0
	v_mov_b32_e32 v124, v0
	v_mov_b32_e32 v125, v0
	v_mov_b32_e32 v126, v0
	v_mov_b32_e32 v127, v0
	.p2alignl 6, 3212836864

;     __device__ __forceinline__ size_t aoff(const Unit& u, size_t ts, int) const { return (size_t)u.pm * ts; }
;     __device__ __forceinline__ size_t boff(const Unit& u, size_t ts, int) const { return (size_t)u.pn * ts; }
;     __device__ __forceinline__ size_t aoff(const Unit& u, size_t ts, int K) const { return (size_t)(u.pm & 15) * ts + (size_t)(u.pm >> 4) * K * 2; }
;     __device__ __forceinline__ size_t boff(const Unit& u, size_t ts, int K) const { return (size_t)u.pn * ts + (size_t)(u.pm >> 4) * K * 2; }
; template <class Epi, class Sched, bool ALIGN_EPI = false, bool SP2 = false>
; __device__ __forceinline__ void gemm_phase(PG8_LAS unsigned char* lds, const Gemm g, const Sched& S, const Epi& E) {
;     ...
;         const bool has_next = S.next(ui + 1, nxt);
;         const char* nA = has_next ? (const char*)g.A + S.aoff(nxt, tstepA, K) : cA; const char* nB = has_next ? (const char*)g.Bt + S.boff(nxt, tstepB, K) : cB;
;         for (int t = 0; t < nt; t += 2) {
;             const bool last = (t == nt - 2);
;             const char* a1 = cA + (size_t)(t + 1) * kstep;
;             const char* a2 = last ? nA : cA + (size_t)(t + 2) * kstep; const char* b2 = last ? nB : cB + (size_t)(t + 2) * kstep;
;             const char* a3 = a2 + kstep; const char* b3 = b2 + kstep;
;     ...
;         for (int a = 0; a < 2; ++a)
; #pragma unroll
;             for (int b = 0; b < 2; ++b)
; #pragma unroll
;                 for (int m = 0; m < 4; ++m)
; #pragma unroll
;                     for (int n = 0; n < 2; ++n) acc[a][b][m][n] = (f32x4){0.f, 0.f, 0.f, 0.f};
;         cur = nxt; cA = nA; cB = nB; ++ui;
.LBB0_927:
	s_ashr_i32 s77, s76, 31
	s_lshl_b64 s[28:29], s[76:77], 19
	s_add_u32 s80, s72, s28
	s_addc_u32 s81, s73, s29
	s_ashr_i32 s69, s68, 31
	s_lshl_b64 s[28:29], s[68:69], 19
	s_add_u32 s82, s22, s28
	v_mov_b32_e32 v127, 0
	s_addc_u32 s83, s23, s29
	s_andn2_b64 vcc, exec, s[48:49]
	v_mov_b32_e32 v126, v127
	v_mov_b32_e32 v125, v127
	v_mov_b32_e32 v124, v127
	v_mov_b32_e32 v123, v127
	v_mov_b32_e32 v122, v127
	v_mov_b32_e32 v121, v127
	v_mov_b32_e32 v120, v127
	v_mov_b32_e32 v111, v127
	v_mov_b32_e32 v110, v127
	v_mov_b32_e32 v109, v127
	v_mov_b32_e32 v108, v127
	v_mov_b32_e32 v107, v127
	v_mov_b32_e32 v106, v127
	v_mov_b32_e32 v105, v127
	v_mov_b32_e32 v104, v127
	v_mov_b32_e32 v95, v127
	v_mov_b32_e32 v94, v127
	v_mov_b32_e32 v93, v127
	v_mov_b32_e32 v92, v127
	v_mov_b32_e32 v91, v127
	v_mov_b32_e32 v90, v127
	v_mov_b32_e32 v89, v127
	v_mov_b32_e32 v88, v127
	v_mov_b32_e32 v79, v127
	v_mov_b32_e32 v78, v127
	v_mov_b32_e32 v77, v127
	v_mov_b32_e32 v76, v127
	v_mov_b32_e32 v75, v127
	v_mov_b32_e32 v74, v127
	v_mov_b32_e32 v73, v127
	v_mov_b32_e32 v72, v127
	v_mov_b32_e32 v119, v127
	v_mov_b32_e32 v118, v127
	v_mov_b32_e32 v117, v127
	v_mov_b32_e32 v116, v127
	v_mov_b32_e32 v115, v127
	v_mov_b32_e32 v114, v127
	v_mov_b32_e32 v113, v127
	v_mov_b32_e32 v112, v127
	v_mov_b32_e32 v103, v127
	v_mov_b32_e32 v102, v127
	v_mov_b32_e32 v101, v127
	v_mov_b32_e32 v100, v127
	v_mov_b32_e32 v99, v127
	v_mov_b32_e32 v98, v127
	v_mov_b32_e32 v97, v127
	v_mov_b32_e32 v96, v127
	v_mov_b32_e32 v87, v127
	v_mov_b32_e32 v86, v127
	v_mov_b32_e32 v85, v127
	v_mov_b32_e32 v84, v127
	v_mov_b32_e32 v83, v127
	v_mov_b32_e32 v82, v127
	v_mov_b32_e32 v81, v127
	v_mov_b32_e32 v80, v127
	v_mov_b32_e32 v71, v127
	v_mov_b32_e32 v70, v127
	v_mov_b32_e32 v69, v127
	v_mov_b32_e32 v68, v127
	v_mov_b32_e32 v67, v127
	v_mov_b32_e32 v66, v127
	v_mov_b32_e32 v65, v127
	v_mov_b32_e32 v64, v127
	v_mov_b32_e32 v63, v127
	v_mov_b32_e32 v62, v127
	v_mov_b32_e32 v61, v127
	v_mov_b32_e32 v60, v127
	v_mov_b32_e32 v59, v127
	v_mov_b32_e32 v58, v127
	v_mov_b32_e32 v57, v127
	v_mov_b32_e32 v56, v127
	v_mov_b32_e32 v47, v127
	v_mov_b32_e32 v46, v127
	v_mov_b32_e32 v45, v127
	v_mov_b32_e32 v44, v127
	v_mov_b32_e32 v43, v127
	v_mov_b32_e32 v42, v127
	v_mov_b32_e32 v41, v127
	v_mov_b32_e32 v40, v127
	v_mov_b32_e32 v31, v127
	v_mov_b32_e32 v30, v127
	v_mov_b32_e32 v29, v127
	v_mov_b32_e32 v28, v127
	v_mov_b32_e32 v27, v127
	v_mov_b32_e32 v26, v127
	v_mov_b32_e32 v25, v127
	v_mov_b32_e32 v24, v127
	v_mov_b32_e32 v15, v127
	v_mov_b32_e32 v14, v127
	v_mov_b32_e32 v13, v127
	v_mov_b32_e32 v12, v127
	v_mov_b32_e32 v11, v127
	v_mov_b32_e32 v10, v127
	v_mov_b32_e32 v9, v127
	v_mov_b32_e32 v8, v127
	v_mov_b32_e32 v55, v127
	v_mov_b32_e32 v54, v127
	v_mov_b32_e32 v53, v127
	v_mov_b32_e32 v52, v127
	v_mov_b32_e32 v51, v127
	v_mov_b32_e32 v50, v127
	v_mov_b32_e32 v49, v127
	v_mov_b32_e32 v48, v127
	v_mov_b32_e32 v39, v127
	v_mov_b32_e32 v38, v127
	v_mov_b32_e32 v37, v127
	v_mov_b32_e32 v36, v127
	v_mov_b32_e32 v35, v127
	v_mov_b32_e32 v34, v127
	v_mov_b32_e32 v33, v127
	v_mov_b32_e32 v32, v127
	v_mov_b32_e32 v23, v127
	v_mov_b32_e32 v22, v127
	v_mov_b32_e32 v21, v127
	v_mov_b32_e32 v20, v127
	v_mov_b32_e32 v19, v127
	v_mov_b32_e32 v18, v127
	v_mov_b32_e32 v17, v127
	v_mov_b32_e32 v16, v127
	v_mov_b32_e32 v7, v127
	v_mov_b32_e32 v6, v127
	v_mov_b32_e32 v5, v127
	v_mov_b32_e32 v4, v127
	v_mov_b32_e32 v3, v127
	v_mov_b32_e32 v2, v127
	v_mov_b32_e32 v1, v127
	v_mov_b32_e32 v0, v127
	s_cbranch_vccnz .LBB0_930
	s_and_b64 s[28:29], s[40:41], exec
	s_cselect_b32 s28, s81, s85
	s_cselect_b32 s29, s80, s84
	s_cselect_b32 s33, s83, s87
	s_cselect_b32 s43, s82, s86
	s_add_u32 s84, s84, 0x40080
	s_addc_u32 s85, s85, 0
	s_add_u32 s45, s86, 0x100
	v_mov_b32_e32 v0, 0
	s_addc_u32 s55, s87, 0
	s_mov_b32 s58, 0
	v_mov_b32_e32 v1, v0
	v_mov_b32_e32 v2, v0
	v_mov_b32_e32 v3, v0
	v_mov_b32_e32 v4, v0
	v_mov_b32_e32 v5, v0
	v_mov_b32_e32 v6, v0
	v_mov_b32_e32 v7, v0
	v_mov_b32_e32 v16, v0
	v_mov_b32_e32 v17, v0
	v_mov_b32_e32 v18, v0
	v_mov_b32_e32 v19, v0
	v_mov_b32_e32 v20, v0
	v_mov_b32_e32 v21, v0
	v_mov_b32_e32 v22, v0
	v_mov_b32_e32 v23, v0
	v_mov_b32_e32 v32, v0
	v_mov_b32_e32 v33, v0
	v_mov_b32_e32 v34, v0
	v_mov_b32_e32 v35, v0
	v_mov_b32_e32 v36, v0
	v_mov_b32_e32 v37, v0
	v_mov_b32_e32 v38, v0
	v_mov_b32_e32 v39, v0
	v_mov_b32_e32 v48, v0
	v_mov_b32_e32 v49, v0
	v_mov_b32_e32 v50, v0
	v_mov_b32_e32 v51, v0
	v_mov_b32_e32 v52, v0
	v_mov_b32_e32 v53, v0
	v_mov_b32_e32 v54, v0
	v_mov_b32_e32 v55, v0
	v_mov_b32_e32 v8, v0
	v_mov_b32_e32 v9, v0
	v_mov_b32_e32 v10, v0
	v_mov_b32_e32 v11, v0
	v_mov_b32_e32 v12, v0
	v_mov_b32_e32 v13, v0
	v_mov_b32_e32 v14, v0
	v_mov_b32_e32 v15, v0
	v_mov_b32_e32 v24, v0
	v_mov_b32_e32 v25, v0
	v_mov_b32_e32 v26, v0
	v_mov_b32_e32 v27, v0
	v_mov_b32_e32 v28, v0
	v_mov_b32_e32 v29, v0
	v_mov_b32_e32 v30, v0
	v_mov_b32_e32 v31, v0
	v_mov_b32_e32 v40, v0
	v_mov_b32_e32 v41, v0
	v_mov_b32_e32 v42, v0
	v_mov_b32_e32 v43, v0
	v_mov_b32_e32 v44, v0
	v_mov_b32_e32 v45, v0
	v_mov_b32_e32 v46, v0
	v_mov_b32_e32 v47, v0
	v_mov_b32_e32 v56, v0
	v_mov_b32_e32 v57, v0
	v_mov_b32_e32 v58, v0
	v_mov_b32_e32 v59, v0
	v_mov_b32_e32 v60, v0
	v_mov_b32_e32 v61, v0
	v_mov_b32_e32 v62, v0
	v_mov_b32_e32 v63, v0
	v_mov_b32_e32 v64, v0
	v_mov_b32_e32 v65, v0
	v_mov_b32_e32 v66, v0
	v_mov_b32_e32 v67, v0
	v_mov_b32_e32 v68, v0
	v_mov_b32_e32 v69, v0
	v_mov_b32_e32 v70, v0
	v_mov_b32_e32 v71, v0
	v_mov_b32_e32 v80, v0
	v_mov_b32_e32 v81, v0
	v_mov_b32_e32 v82, v0
	v_mov_b32_e32 v83, v0
	v_mov_b32_e32 v84, v0
	v_mov_b32_e32 v85, v0
	v_mov_b32_e32 v86, v0
	v_mov_b32_e32 v87, v0
	v_mov_b32_e32 v96, v0
	v_mov_b32_e32 v97, v0
	v_mov_b32_e32 v98, v0
	v_mov_b32_e32 v99, v0
	v_mov_b32_e32 v100, v0
	v_mov_b32_e32 v101, v0
	v_mov_b32_e32 v102, v0
	v_mov_b32_e32 v103, v0
	v_mov_b32_e32 v112, v0
	v_mov_b32_e32 v113, v0
	v_mov_b32_e32 v114, v0
	v_mov_b32_e32 v115, v0
	v_mov_b32_e32 v116, v0
	v_mov_b32_e32 v117, v0
	v_mov_b32_e32 v118, v0
	v_mov_b32_e32 v119, v0
	v_mov_b32_e32 v72, v0
	v_mov_b32_e32 v73, v0
	v_mov_b32_e32 v74, v0
	v_mov_b32_e32 v75, v0
	v_mov_b32_e32 v76, v0
	v_mov_b32_e32 v77, v0
	v_mov_b32_e32 v78, v0
	v_mov_b32_e32 v79, v0
	v_mov_b32_e32 v88, v0
	v_mov_b32_e32 v89, v0
	v_mov_b32_e32 v90, v0
	v_mov_b32_e32 v91, v0
	v_mov_b32_e32 v92, v0
	v_mov_b32_e32 v93, v0
	v_mov_b32_e32 v94, v0
	v_mov_b32_e32 v95, v0
	v_mov_b32_e32 v104, v0
	v_mov_b32_e32 v105, v0
	v_mov_b32_e32 v106, v0
	v_mov_b32_e32 v107, v0
	v_mov_b32_e32 v108, v0
	v_mov_b32_e32 v109, v0
	v_mov_b32_e32 v110, v0
	v_mov_b32_e32 v111, v0
	v_mov_b32_e32 v120, v0
	v_mov_b32_e32 v121, v0
	v_mov_b32_e32 v122, v0
	v_mov_b32_e32 v123, v0
	v_mov_b32_e32 v124, v0
	v_mov_b32_e32 v125, v0
	v_mov_b32_e32 v126, v0
	v_mov_b32_e32 v127, v0
	.p2alignl 6, 3212836864

;     __device__ __forceinline__ size_t aoff(const Unit& u, size_t ts, int) const { return (size_t)u.pm * ts; }
;     __device__ __forceinline__ size_t boff(const Unit& u, size_t ts, int) const { return (size_t)u.pn * ts; }
;     __device__ __forceinline__ size_t aoff(const Unit& u, size_t ts, int K) const { return (size_t)(u.pm & 15) * ts + (size_t)(u.pm >> 4) * K * 2; }
;     __device__ __forceinline__ size_t boff(const Unit& u, size_t ts, int K) const { return (size_t)u.pn * ts + (size_t)(u.pm >> 4) * K * 2; }
; template <class Epi, class Sched, bool ALIGN_EPI = false, bool SP2 = false>
; __device__ __forceinline__ void gemm_phase(PG8_LAS unsigned char* lds, const Gemm g, const Sched& S, const Epi& E) {
;     ...
;         const bool has_next = S.next(ui + 1, nxt);
;         const char* nA = has_next ? (const char*)g.A + S.aoff(nxt, tstepA, K) : cA; const char* nB = has_next ? (const char*)g.Bt + S.boff(nxt, tstepB, K) : cB;
;         for (int t = 0; t < nt; t += 2) {
;             const bool last = (t == nt - 2);
;             const char* a1 = cA + (size_t)(t + 1) * kstep;
;             const char* a2 = last ? nA : cA + (size_t)(t + 2) * kstep; const char* b2 = last ? nB : cB + (size_t)(t + 2) * kstep;
;             const char* a3 = a2 + kstep; const char* b3 = b2 + kstep;
;     ...
;         for (int a = 0; a < 2; ++a)
; #pragma unroll
;             for (int b = 0; b < 2; ++b)
; #pragma unroll
;                 for (int m = 0; m < 4; ++m)
; #pragma unroll
;                     for (int n = 0; n < 2; ++n) acc[a][b][m][n] = (f32x4){0.f, 0.f, 0.f, 0.f};
;         cur = nxt; cA = nA; cB = nB; ++ui;
.LBB0_1017:
	s_ashr_i32 s53, s52, 31
	s_lshl_b64 s[58:59], s[52:53], 19
	v_readlane_b32 s4, v254, 10
	s_add_u32 s80, s4, s58
	v_readlane_b32 s4, v254, 11
	s_addc_u32 s81, s4, s59
	s_ashr_i32 s49, s48, 31
	s_lshl_b64 s[58:59], s[48:49], 19
	s_add_u32 s82, s72, s58
	v_mov_b32_e32 v123, 0
	s_addc_u32 s83, s73, s59
	s_andn2_b64 vcc, exec, s[42:43]
	v_mov_b32_e32 v122, v123
	v_mov_b32_e32 v121, v123
	v_mov_b32_e32 v120, v123
	v_mov_b32_e32 v127, v123
	v_mov_b32_e32 v126, v123
	v_mov_b32_e32 v125, v123
	v_mov_b32_e32 v124, v123
	v_mov_b32_e32 v119, v123
	v_mov_b32_e32 v118, v123
	v_mov_b32_e32 v117, v123
	v_mov_b32_e32 v116, v123
	v_mov_b32_e32 v115, v123
	v_mov_b32_e32 v114, v123
	v_mov_b32_e32 v113, v123
	v_mov_b32_e32 v112, v123
	v_mov_b32_e32 v111, v123
	v_mov_b32_e32 v110, v123
	v_mov_b32_e32 v109, v123
	v_mov_b32_e32 v108, v123
	v_mov_b32_e32 v107, v123
	v_mov_b32_e32 v106, v123
	v_mov_b32_e32 v105, v123
	v_mov_b32_e32 v104, v123
	v_mov_b32_e32 v103, v123
	v_mov_b32_e32 v102, v123
	v_mov_b32_e32 v101, v123
	v_mov_b32_e32 v100, v123
	v_mov_b32_e32 v99, v123
	v_mov_b32_e32 v98, v123
	v_mov_b32_e32 v97, v123
	v_mov_b32_e32 v96, v123
	v_mov_b32_e32 v63, v123
	v_mov_b32_e32 v62, v123
	v_mov_b32_e32 v61, v123
	v_mov_b32_e32 v60, v123
	v_mov_b32_e32 v59, v123
	v_mov_b32_e32 v58, v123
	v_mov_b32_e32 v57, v123
	v_mov_b32_e32 v56, v123
	v_mov_b32_e32 v55, v123
	v_mov_b32_e32 v54, v123
	v_mov_b32_e32 v53, v123
	v_mov_b32_e32 v52, v123
	v_mov_b32_e32 v51, v123
	v_mov_b32_e32 v50, v123
	v_mov_b32_e32 v49, v123
	v_mov_b32_e32 v48, v123
	v_mov_b32_e32 v47, v123
	v_mov_b32_e32 v46, v123
	v_mov_b32_e32 v45, v123
	v_mov_b32_e32 v44, v123
	v_mov_b32_e32 v43, v123
	v_mov_b32_e32 v42, v123
	v_mov_b32_e32 v41, v123
	v_mov_b32_e32 v40, v123
	v_mov_b32_e32 v39, v123
	v_mov_b32_e32 v38, v123
	v_mov_b32_e32 v37, v123
	v_mov_b32_e32 v36, v123
	v_mov_b32_e32 v35, v123
	v_mov_b32_e32 v34, v123
	v_mov_b32_e32 v33, v123
	v_mov_b32_e32 v32, v123
	v_mov_b32_e32 v95, v123
	v_mov_b32_e32 v94, v123
	v_mov_b32_e32 v93, v123
	v_mov_b32_e32 v92, v123
	v_mov_b32_e32 v91, v123
	v_mov_b32_e32 v90, v123
	v_mov_b32_e32 v89, v123
	v_mov_b32_e32 v88, v123
	v_mov_b32_e32 v87, v123
	v_mov_b32_e32 v86, v123
	v_mov_b32_e32 v85, v123
	v_mov_b32_e32 v84, v123
	v_mov_b32_e32 v83, v123
	v_mov_b32_e32 v82, v123
	v_mov_b32_e32 v81, v123
	v_mov_b32_e32 v80, v123
	v_mov_b32_e32 v79, v123
	v_mov_b32_e32 v78, v123
	v_mov_b32_e32 v77, v123
	v_mov_b32_e32 v76, v123
	v_mov_b32_e32 v75, v123
	v_mov_b32_e32 v74, v123
	v_mov_b32_e32 v73, v123
	v_mov_b32_e32 v72, v123
	v_mov_b32_e32 v71, v123
	v_mov_b32_e32 v70, v123
	v_mov_b32_e32 v69, v123
	v_mov_b32_e32 v68, v123
	v_mov_b32_e32 v67, v123
	v_mov_b32_e32 v66, v123
	v_mov_b32_e32 v65, v123
	v_mov_b32_e32 v64, v123
	v_mov_b32_e32 v31, v123
	v_mov_b32_e32 v30, v123
	v_mov_b32_e32 v29, v123
	v_mov_b32_e32 v28, v123
	v_mov_b32_e32 v27, v123
	v_mov_b32_e32 v26, v123
	v_mov_b32_e32 v25, v123
	v_mov_b32_e32 v24, v123
	v_mov_b32_e32 v23, v123
	v_mov_b32_e32 v22, v123
	v_mov_b32_e32 v21, v123
	v_mov_b32_e32 v20, v123
	v_mov_b32_e32 v19, v123
	v_mov_b32_e32 v18, v123
	v_mov_b32_e32 v17, v123
	v_mov_b32_e32 v16, v123
	v_mov_b32_e32 v15, v123
	v_mov_b32_e32 v14, v123
	v_mov_b32_e32 v13, v123
	v_mov_b32_e32 v12, v123
	v_mov_b32_e32 v11, v123
	v_mov_b32_e32 v10, v123
	v_mov_b32_e32 v9, v123
	v_mov_b32_e32 v8, v123
	v_mov_b32_e32 v7, v123
	v_mov_b32_e32 v6, v123
	v_mov_b32_e32 v5, v123
	v_mov_b32_e32 v4, v123
	v_mov_b32_e32 v3, v123
	v_mov_b32_e32 v2, v123
	v_mov_b32_e32 v1, v123
	v_mov_b32_e32 v0, v123
	s_cbranch_vccnz .LBB0_1020
	s_and_b64 s[58:59], s[38:39], exec
	s_cselect_b32 s49, s81, s85
	s_cselect_b32 s53, s80, s84
	s_cselect_b32 s55, s83, s87
	s_cselect_b32 s58, s82, s86
	s_add_u32 s84, s84, 0x40080
	s_addc_u32 s85, s85, 0
	s_add_u32 s59, s86, 0x100
	v_mov_b32_e32 v0, 0
	s_addc_u32 s61, s87, 0
	s_mov_b32 s62, 0
	v_mov_b32_e32 v1, v0
	v_mov_b32_e32 v2, v0
	v_mov_b32_e32 v3, v0
	v_mov_b32_e32 v4, v0
	v_mov_b32_e32 v5, v0
	v_mov_b32_e32 v6, v0
	v_mov_b32_e32 v7, v0
	v_mov_b32_e32 v8, v0
	v_mov_b32_e32 v9, v0
	v_mov_b32_e32 v10, v0
	v_mov_b32_e32 v11, v0
	v_mov_b32_e32 v12, v0
	v_mov_b32_e32 v13, v0
	v_mov_b32_e32 v14, v0
	v_mov_b32_e32 v15, v0
	v_mov_b32_e32 v16, v0
	v_mov_b32_e32 v17, v0
	v_mov_b32_e32 v18, v0
	v_mov_b32_e32 v19, v0
	v_mov_b32_e32 v20, v0
	v_mov_b32_e32 v21, v0
	v_mov_b32_e32 v22, v0
	v_mov_b32_e32 v23, v0
	v_mov_b32_e32 v24, v0
	v_mov_b32_e32 v25, v0
	v_mov_b32_e32 v26, v0
	v_mov_b32_e32 v27, v0
	v_mov_b32_e32 v28, v0
	v_mov_b32_e32 v29, v0
	v_mov_b32_e32 v30, v0
	v_mov_b32_e32 v31, v0
	v_mov_b32_e32 v64, v0
	v_mov_b32_e32 v65, v0
	v_mov_b32_e32 v66, v0
	v_mov_b32_e32 v67, v0
	v_mov_b32_e32 v68, v0
	v_mov_b32_e32 v69, v0
	v_mov_b32_e32 v70, v0
	v_mov_b32_e32 v71, v0
	v_mov_b32_e32 v72, v0
	v_mov_b32_e32 v73, v0
	v_mov_b32_e32 v74, v0
	v_mov_b32_e32 v75, v0
	v_mov_b32_e32 v76, v0
	v_mov_b32_e32 v77, v0
	v_mov_b32_e32 v78, v0
	v_mov_b32_e32 v79, v0
	v_mov_b32_e32 v80, v0
	v_mov_b32_e32 v81, v0
	v_mov_b32_e32 v82, v0
	v_mov_b32_e32 v83, v0
	v_mov_b32_e32 v84, v0
	v_mov_b32_e32 v85, v0
	v_mov_b32_e32 v86, v0
	v_mov_b32_e32 v87, v0
	v_mov_b32_e32 v88, v0
	v_mov_b32_e32 v89, v0
	v_mov_b32_e32 v90, v0
	v_mov_b32_e32 v91, v0
	v_mov_b32_e32 v92, v0
	v_mov_b32_e32 v93, v0
	v_mov_b32_e32 v94, v0
	v_mov_b32_e32 v95, v0
	v_mov_b32_e32 v32, v0
	v_mov_b32_e32 v33, v0
	v_mov_b32_e32 v34, v0
	v_mov_b32_e32 v35, v0
	v_mov_b32_e32 v36, v0
	v_mov_b32_e32 v37, v0
	v_mov_b32_e32 v38, v0
	v_mov_b32_e32 v39, v0
	v_mov_b32_e32 v40, v0
	v_mov_b32_e32 v41, v0
	v_mov_b32_e32 v42, v0
	v_mov_b32_e32 v43, v0
	v_mov_b32_e32 v44, v0
	v_mov_b32_e32 v45, v0
	v_mov_b32_e32 v46, v0
	v_mov_b32_e32 v47, v0
	v_mov_b32_e32 v48, v0
	v_mov_b32_e32 v49, v0
	v_mov_b32_e32 v50, v0
	v_mov_b32_e32 v51, v0
	v_mov_b32_e32 v52, v0
	v_mov_b32_e32 v53, v0
	v_mov_b32_e32 v54, v0
	v_mov_b32_e32 v55, v0
	v_mov_b32_e32 v56, v0
	v_mov_b32_e32 v57, v0
	v_mov_b32_e32 v58, v0
	v_mov_b32_e32 v59, v0
	v_mov_b32_e32 v60, v0
	v_mov_b32_e32 v61, v0
	v_mov_b32_e32 v62, v0
	v_mov_b32_e32 v63, v0
	v_mov_b32_e32 v96, v0
	v_mov_b32_e32 v97, v0
	v_mov_b32_e32 v98, v0
	v_mov_b32_e32 v99, v0
	v_mov_b32_e32 v100, v0
	v_mov_b32_e32 v101, v0
	v_mov_b32_e32 v102, v0
	v_mov_b32_e32 v103, v0
	v_mov_b32_e32 v104, v0
	v_mov_b32_e32 v105, v0
	v_mov_b32_e32 v106, v0
	v_mov_b32_e32 v107, v0
	v_mov_b32_e32 v108, v0
	v_mov_b32_e32 v109, v0
	v_mov_b32_e32 v110, v0
	v_mov_b32_e32 v111, v0
	v_mov_b32_e32 v112, v0
	v_mov_b32_e32 v113, v0
	v_mov_b32_e32 v114, v0
	v_mov_b32_e32 v115, v0
	v_mov_b32_e32 v116, v0
	v_mov_b32_e32 v117, v0
	v_mov_b32_e32 v118, v0
	v_mov_b32_e32 v119, v0
	v_mov_b32_e32 v124, v0
	v_mov_b32_e32 v125, v0
	v_mov_b32_e32 v126, v0
	v_mov_b32_e32 v127, v0
	v_mov_b32_e32 v120, v0
	v_mov_b32_e32 v121, v0
	v_mov_b32_e32 v122, v0
	v_mov_b32_e32 v123, v0
	.p2alignl 6, 3212836864

; #define WAIT_BAR(N) asm volatile("s_waitcnt vmcnt(" #N ") lgkmcnt(0)\n\ts_barrier" ::: "memory")
; __device__ __forceinline__ int pi_row(int i) { return (i & ~12) | ((i & 4) << 1) | ((i & 8) >> 1); }
; #define D_ISSUE() do { D_ISSUE_A(); D_ISSUE_B(); } while (0)
; __device__ __forceinline__ void attn_diff_unit(LAS unsigned char* lds, const bf16_t* __restrict__ Q, const bf16_t* __restrict__ Kb, const bf16_t* __restrict__ VT, bf16_t* O,
;                                                int qrow0, int b, int h, int ntiles, float lam, const float* subln_g) {
;     ...
;     const bf16_t* kbase = Kb + (size_t)b * KVLEN * D + h * 128; const bf16_t* vbase = VT + (size_t)(b * 1024 + h * 128) * KVLEN;
;     int poff[5], pdst[5]; const bool w0 = (wid == 0);
; #pragma unroll
;     for (int j = 0; j < 5; ++j) { int P = wid + 8 * j; if (P >= 35) P -= 8;
;         const bool isk = (j < 2) || (j == 2 && w0);
;         const int pk = isk ? P : P - 17, g = pk * 64 + lane;
;         const int ik = g / 17, cik = g - ik * 17, iv = g / 9, civ = g - iv * 9;
;         poff[j] = isk ? pi_row(ik) * D + (cik > 15 ? 15 : cik) * 8 : iv * KVLEN + (civ > 7 ? 7 : civ) * 8; pdst[j] = pk * 1024; }
;     int ks3 = 0, vs4 = 0;
;     int tiss = 0;
;     ...
;     const int koff = r32 * DK_STRIDE + (sub * 64 + hi * 8) * 2;
;     const int voff = D_VRING + r32 * DV_STRIDE + hi * 16;
;     D_ISSUE(); D_ISSUE();
;     ...
;     WAIT_BAR(5);
.LBB0_1097:
	s_mul_i32 s14, s2, 0x880000
	v_readlane_b32 s4, v254, 6
	s_mul_hi_i32 s11, s2, 0x880000
	v_readlane_b32 s5, v254, 7
	s_add_u32 s39, s4, s14
	s_addc_u32 s40, s5, s11
	s_lshl_b32 s2, s2, 10
	s_or_b32 s2, s33, s2
	s_mul_hi_i32 s41, s2, 0x2200
	s_mul_i32 s46, s2, 0x2200
	s_add_i32 s2, s12, -8
	s_cmp_gt_i32 s12, 34
	s_cselect_b32 s11, s2, s12
	v_lshl_or_b32 v0, s11, 6, v229
	s_mov_b32 s4, 0x78787879
	v_mul_hi_i32 v1, v0, s4
	v_lshrrev_b32_e32 v3, 31, v1
	v_ashrrev_i32_e32 v1, 3, v1
	v_add_u32_e32 v3, v1, v3
	s_movk_i32 s5, 0xffef
	v_mad_u64_u32 v[0:1], s[34:35], v3, s5, v[0:1]
	v_and_b32_e32 v1, 0x3ffff3, v3
	v_lshlrev_b32_e32 v4, 1, v3
	v_lshrrev_b32_e32 v3, 1, v3
	s_lshl_b32 s14, s11, 10
	s_add_i32 s11, s12, 8
	v_and_b32_e32 v4, 8, v4
	v_and_b32_e32 v3, 4, v3
	v_min_i32_e32 v0, 15, v0
	s_cmp_gt_i32 s12, 26
	v_or3_b32 v1, v1, v4, v3
	v_lshlrev_b32_e32 v0, 3, v0
	s_cselect_b32 s11, s12, s11
	v_lshl_add_u32 v212, v1, 10, v0
	v_lshl_or_b32 v0, s11, 6, v229
	v_mul_hi_i32 v1, v0, s4
	v_lshrrev_b32_e32 v3, 31, v1
	v_ashrrev_i32_e32 v1, 3, v1
	v_add_u32_e32 v3, v1, v3
	v_mad_u64_u32 v[0:1], s[34:35], v3, s5, v[0:1]
	s_lshl_b32 s16, s11, 10
	s_lshl_b32 s3, s3, 10
	v_and_b32_e32 v1, 0x3ffff3, v3
	v_lshlrev_b32_e32 v4, 1, v3
	v_lshrrev_b32_e32 v3, 1, v3
	s_cmp_gt_i32 s12, 10
	v_and_b32_e32 v4, 8, v4
	v_and_b32_e32 v3, 4, v3
	v_min_i32_e32 v0, 15, v0
	s_cselect_b32 s11, 16, 24
	s_sub_i32 s44, s12, 17
	v_or3_b32 v1, v1, v4, v3
	v_lshlrev_b32_e32 v0, 3, v0
	s_add_i32 s11, s44, s11
	v_lshl_add_u32 v214, v1, 10, v0
	v_lshl_or_b32 v0, s11, 6, v229
	s_mov_b32 s5, 0x38e38e39
	v_mul_hi_i32 v1, v0, s5
	v_lshrrev_b32_e32 v3, 31, v1
	v_ashrrev_i32_e32 v1, 1, v1
	s_lshl_b32 s11, s11, 10
	v_add_u32_e32 v3, v1, v3
	s_cmp_gt_i32 s12, 2
	v_mad_u64_u32 v[0:1], s[34:35], v3, -9, v[0:1]
	s_movk_i32 s4, 0x1100
	s_cselect_b32 s12, 24, 32
	v_mul_lo_u32 v1, v3, s4
	v_min_i32_e32 v0, 7, v0
	s_add_i32 s44, s44, s12
	v_lshl_add_u32 v208, v0, 3, v1
	v_lshl_or_b32 v0, s44, 6, v229
	v_mul_hi_i32 v1, v0, s5
	v_lshrrev_b32_e32 v3, 31, v1
	v_ashrrev_i32_e32 v1, 1, v1
	v_add_u32_e32 v3, v1, v3
	s_lshl_b32 s12, s44, 10
	s_lshl_b32 s33, s33, 1
	v_mad_u64_u32 v[0:1], s[34:35], v3, -9, v[0:1]
	s_add_u32 s44, s39, s33
	v_min_i32_e32 v0, 7, v0
	v_mul_lo_u32 v1, v3, s4
	s_addc_u32 s45, s40, 0
	v_readlane_b32 s4, v254, 8
	v_ashrrev_i32_e32 v213, 31, v212
	v_lshlrev_b32_e32 v2, 3, v230
	v_lshl_add_u32 v210, v0, 3, v1
	v_readlane_b32 s5, v254, 9
	s_add_u32 s34, s4, s46
	v_lshlrev_b64 v[0:1], 1, v[212:213]
	s_addc_u32 s35, s5, s41
	v_or_b32_e32 v12, s38, v2
	v_lshl_add_u64 v[2:3], s[44:45], 0, v[0:1]
	s_add_i32 s33, s14, 0
	v_ashrrev_i32_e32 v215, 31, v214
	s_mov_b32 s38, m0
	s_mov_b32 m0, s33
	s_nop 0
	global_load_lds_dwordx4 v[2:3], off
	s_mov_b32 m0, s38
	v_lshlrev_b64 v[2:3], 1, v[214:215]
	s_add_i32 s33, s16, 0
	v_lshl_add_u64 v[4:5], s[44:45], 0, v[2:3]
	s_mov_b32 s38, m0
	s_mov_b32 m0, s33
	s_nop 0
	global_load_lds_dwordx4 v[4:5], off
	s_mov_b32 m0, s38
	s_and_b64 s[38:39], s[42:43], exec
	v_ashrrev_i32_e32 v207, 31, v206
	s_cselect_b32 s39, s45, s35
	s_cselect_b32 s38, s44, s34
	v_lshlrev_b64 v[4:5], 1, v[206:207]
	v_lshl_add_u64 v[6:7], s[38:39], 0, v[4:5]
	s_add_i32 s29, s29, s3
	v_ashrrev_i32_e32 v209, 31, v208
	v_readlane_b32 s4, v255, 5
	s_mov_b32 s33, m0
	s_mov_b32 m0, s29
	s_nop 0
	global_load_lds_dwordx4 v[6:7], off
	s_mov_b32 m0, s33
	v_lshlrev_b64 v[6:7], 1, v[208:209]
	s_add_i32 s29, s11, s4
	v_lshl_add_u64 v[8:9], s[34:35], 0, v[6:7]
	s_mov_b32 s33, m0
	s_mov_b32 m0, s29
	s_nop 0
	global_load_lds_dwordx4 v[8:9], off
	s_mov_b32 m0, s33
	v_ashrrev_i32_e32 v211, 31, v210
	s_add_i32 s29, s12, s4
	v_lshlrev_b64 v[8:9], 1, v[210:211]
	s_add_u32 s38, s44, 0x20000
	v_lshl_add_u64 v[10:11], s[34:35], 0, v[8:9]
	s_mov_b32 s33, m0
	s_mov_b32 m0, s29
	s_nop 0
	global_load_lds_dwordx4 v[10:11], off
	s_mov_b32 m0, s33
	s_addc_u32 s39, s45, 0
	s_add_i32 s29, 0, 0x4400
	v_lshl_add_u64 v[10:11], s[38:39], 0, v[0:1]
	s_add_i32 s33, s14, s29
	s_mov_b32 s40, m0
	s_mov_b32 m0, s33
	s_nop 0
	global_load_lds_dwordx4 v[10:11], off
	s_mov_b32 m0, s40
	s_add_i32 s29, s16, s29
	s_add_u32 s40, s34, 0x80
	s_addc_u32 s41, s35, 0
	s_and_b64 s[46:47], s[42:43], exec
	v_lshl_add_u64 v[10:11], s[38:39], 0, v[2:3]
	s_mov_b32 s33, m0
	s_mov_b32 m0, s29
	s_nop 0
	global_load_lds_dwordx4 v[10:11], off
	s_mov_b32 m0, s33
	s_cselect_b32 s39, s39, s41
	s_cselect_b32 s38, s38, s40
	s_add_i32 s17, s17, s3
	v_readlane_b32 s4, v255, 6
	v_lshl_add_u64 v[10:11], s[38:39], 0, v[4:5]
	s_mov_b32 s29, m0
	s_mov_b32 m0, s17
	s_nop 0
	global_load_lds_dwordx4 v[10:11], off
	s_mov_b32 m0, s29
	s_add_i32 s17, s11, s4
	v_lshl_add_u64 v[10:11], s[40:41], 0, v[6:7]
	s_mov_b32 s29, m0
	s_mov_b32 m0, s17
	s_nop 0
	global_load_lds_dwordx4 v[10:11], off
	s_mov_b32 m0, s29
	s_add_i32 s17, s12, s4
	s_add_u32 s38, s44, 0x40000
	v_lshl_add_u64 v[10:11], s[40:41], 0, v[8:9]
	s_mov_b32 s29, m0
	s_mov_b32 m0, s17
	s_nop 0
	global_load_lds_dwordx4 v[10:11], off
	s_mov_b32 m0, s29
	s_addc_u32 s39, s45, 0
	s_add_i32 s17, 0, 0x8800
	s_add_i32 s29, s14, s17
	s_add_i32 s17, s16, s17
	s_add_u32 s40, s34, 0x100
	s_waitcnt vmcnt(5) lgkmcnt(0)
	s_barrier
; #define LAS __attribute__((address_space(3)))
; #define MFMA32(a, b, c) __builtin_amdgcn_mfma_f32_32x32x16_bf16((a), (b), (c), 0, 0, 0)
; #define D_ISSUE() do { D_ISSUE_A(); D_ISSUE_B(); } while (0)
; template <int NKD, int KSTRIDE> __device__ __forceinline__ void att_qk(const LAS unsigned char* kb, const bf16x8 (&qr)[NKD], f32x16& c0, f32x16& c1) {
;     f32x16 z;
; #pragma unroll
;     for (int r = 0; r < 16; ++r) z[r] = 0.f;
; #pragma unroll
;     for (int d0 = 0; d0 < NKD; ++d0) { const bf16x8 k0 = *(const LAS bf16x8*)(kb + d0 * 32), k1 = *(const LAS bf16x8*)(kb + 32 * KSTRIDE + d0 * 32);
;         c0 = MFMA32(k0, qr[d0], d0 == 0 ? z : c0); c1 = MFMA32(k1, qr[d0], d0 == 0 ? z : c1); }
; }
; __device__ __forceinline__ void attn_diff_unit(LAS unsigned char* lds, const bf16_t* __restrict__ Q, const bf16_t* __restrict__ Kb, const bf16_t* __restrict__ VT, bf16_t* O,
;                                                int qrow0, int b, int h, int ntiles, float lam, const float* subln_g) {
;     ...
;     f32x16 o[4];
; #pragma unroll
;     for (int k = 0; k < 4; ++k)
; #pragma unroll
;         for (int r = 0; r < 16; ++r) o[k][r] = 0.f;
;     ...
;     D_ISSUE();
;     att_qk<4, DK_STRIDE>(lds + koff, qr, pA0, pA1);
	s_addc_u32 s41, s35, 0
	v_lshl_add_u64 v[0:1], s[38:39], 0, v[0:1]
	s_mov_b32 s33, m0
	s_mov_b32 m0, s29
	s_nop 0
	global_load_lds_dwordx4 v[0:1], off
	s_mov_b32 m0, s33
	s_and_b64 s[46:47], s[42:43], exec
	v_lshl_add_u64 v[0:1], s[38:39], 0, v[2:3]
	s_mov_b32 s29, m0
	s_mov_b32 m0, s17
	s_nop 0
	global_load_lds_dwordx4 v[0:1], off
	s_mov_b32 m0, s29
	s_cselect_b32 s39, s39, s41
	s_cselect_b32 s38, s38, s40
	v_mul_u32_u24_e32 v10, 0x110, v228
	v_lshl_add_u64 v[0:1], s[38:39], 0, v[4:5]
	s_add_i32 s13, s13, s3
	s_mov_b32 s17, m0
	s_mov_b32 m0, s13
	s_nop 0
	global_load_lds_dwordx4 v[0:1], off
	s_mov_b32 m0, s17
	v_readlane_b32 s4, v255, 7
	v_lshl_add_u32 v248, v12, 1, v10
	v_lshl_add_u64 v[0:1], s[40:41], 0, v[6:7]
	s_add_i32 s13, s11, s4
	s_mov_b32 s17, m0
	s_mov_b32 m0, s13
	s_nop 0
	global_load_lds_dwordx4 v[0:1], off
	s_mov_b32 m0, s17
	v_lshl_add_u64 v[0:1], s[40:41], 0, v[8:9]
	s_add_i32 s13, s12, s4
	s_mov_b32 s17, m0
	s_mov_b32 m0, s13
	s_nop 0
	global_load_lds_dwordx4 v[0:1], off
	s_mov_b32 m0, s17
	v_add_u32_e32 v249, 0, v248
	ds_read_b128 v[16:19], v249 offset:8704
	ds_read_b128 v[20:23], v249
	ds_read_b128 v[48:51], v249 offset:32
	ds_read_b128 v[52:55], v249 offset:8736
	s_waitcnt lgkmcnt(2)
	v_mfma_f32_32x32x16_bf16 v[32:47], v[20:23], v[142:145], 0
	v_cmp_lt_i32_e32 vcc, v221, v220
	s_mov_b32 s80, 0
	s_mov_b32 s81, s80
	s_mov_b32 s82, s80
	s_mov_b32 s83, s80
	s_mov_b32 s84, s80
	s_mov_b32 s85, s80
	v_mfma_f32_32x32x16_bf16 v[16:31], v[16:19], v[142:145], 0
	s_mov_b32 s86, s80
	s_mov_b32 s87, s80
	s_mov_b32 s88, s80
	s_mov_b32 s89, s80
	s_mov_b32 s90, s80
	s_mov_b32 s91, s80
	s_mov_b32 s92, s80
	s_waitcnt lgkmcnt(1)
	v_mfma_f32_32x32x16_bf16 v[32:47], v[48:51], v[138:141], v[32:47]
	s_mov_b32 s93, s80
	s_mov_b32 s94, s80
	s_mov_b32 s95, s80
	v_mov_b64_e32 v[0:1], s[80:81]
	s_movk_i32 s4, 0x90
	v_mov_b64_e32 v[14:15], s[94:95]
	v_mad_u32_u24 v232, v228, s4, v194
	s_waitcnt lgkmcnt(0)
	v_mfma_f32_32x32x16_bf16 v[16:31], v[52:55], v[138:141], v[16:31]
	ds_read_b128 v[48:51], v249 offset:64
	ds_read_b128 v[52:55], v249 offset:8768
	s_cmpk_lt_u32 s8, 0x100
	s_movk_i32 s4, 0x100
	v_mov_b64_e32 v[2:3], s[82:83]
	v_mov_b64_e32 v[4:5], s[84:85]
	v_mov_b64_e32 v[6:7], s[86:87]
	v_mov_b64_e32 v[8:9], s[88:89]
	s_waitcnt lgkmcnt(1)
	v_mfma_f32_32x32x16_bf16 v[32:47], v[48:51], v[134:137], v[32:47]
	v_mov_b64_e32 v[10:11], s[90:91]
	v_mov_b64_e32 v[12:13], s[92:93]
	s_cselect_b64 s[48:49], -1, 0
	s_cmpk_gt_u32 s8, 0xff
	s_mov_b32 s2, 3
	s_mov_b32 s28, 1
	v_add_u32_e32 v200, 0, v232
	s_waitcnt lgkmcnt(0)
	v_mfma_f32_32x32x16_bf16 v[16:31], v[52:55], v[134:137], v[16:31]
	ds_read_b128 v[48:51], v249 offset:96
	ds_read_b128 v[52:55], v249 offset:8800
	s_waitcnt vmcnt(5) lgkmcnt(0)
	s_barrier
; #define WAIT_BAR(N) asm volatile("s_waitcnt vmcnt(" #N ") lgkmcnt(0)\n\ts_barrier" ::: "memory")
; #define D_ISSUE() do { D_ISSUE_A(); D_ISSUE_B(); } while (0)
; __device__ __forceinline__ void att_first(f32x16& c0, f32x16& c1, float& mhat) {
;     float rm = fmaxf(c0[0], c1[0]);
; #pragma unroll
;     for (int r = 1; r < 16; ++r) rm = fmaxf(rm, fmaxf(c0[r], c1[r]));
;     rm = fmaxf(rm, __shfl_xor(rm, 32)); mhat = rm;
; #pragma unroll
;     for (int r = 0; r < 16; ++r) { c0[r] = __builtin_amdgcn_exp2f(c0[r] - mhat); c1[r] = __builtin_amdgcn_exp2f(c1[r] - mhat); }
; }
; __device__ __forceinline__ void attn_diff_unit(LAS unsigned char* lds, const bf16_t* __restrict__ Q, const bf16_t* __restrict__ Kb, const bf16_t* __restrict__ VT, bf16_t* O,
;                                                int qrow0, int b, int h, int ntiles, float lam, const float* subln_g) {
;     ...
;     f32x16 o[4];
; #pragma unroll
;     for (int k = 0; k < 4; ++k)
; #pragma unroll
;         for (int r = 0; r < 16; ++r) o[k][r] = 0.f;
;     float mhat = 0.f, lrun = 0.f, fsc = 1.f;
;     f32x16 pA0, pA1, pB0, pB1; bf16x8 pf[4], vf[8];
;     WAIT_BAR(5);
;     D_ISSUE();
;     att_qk<4, DK_STRIDE>(lds + koff, qr, pA0, pA1);
;     att_first(pA0, pA1, mhat);
;     WAIT_BAR(5);
;     int kc = 1, vc = 0;
	s_cselect_b64 s[52:53], -1, 0
	v_mov_b32_e32 v201, 0
	s_mov_b32 s46, 3
	s_mov_b32 s13, s80
	s_mov_b32 s17, 1
	s_waitcnt lgkmcnt(1)
	v_mfma_f32_32x32x16_bf16 v[32:47], v[48:51], v[130:133], v[32:47]
	v_readlane_b32 s84, v255, 12
	s_waitcnt lgkmcnt(0)
	v_mfma_f32_32x32x16_bf16 v[16:31], v[52:55], v[130:133], v[16:31]
	s_nop 8
	v_max_f32_e32 v49, v33, v33
	v_max_f32_e32 v50, v34, v34
	v_max_f32_e32 v51, v35, v35
	v_max_f32_e32 v48, v17, v17
	v_max_f32_e32 v48, v49, v48
	v_max_f32_e32 v49, v18, v18
	v_max_f32_e32 v49, v50, v49
	v_max_f32_e32 v50, v19, v19
	v_max3_f32 v48, v32, v16, v48
	v_max_f32_e32 v50, v51, v50
	v_max3_f32 v48, v48, v49, v50
	v_max_f32_e32 v49, v20, v20
	v_max_f32_e32 v50, v36, v36
	v_max_f32_e32 v49, v50, v49
	v_max_f32_e32 v50, v21, v21
	v_max_f32_e32 v51, v37, v37
	v_max_f32_e32 v50, v51, v50
	v_max3_f32 v48, v48, v49, v50
	v_max_f32_e32 v49, v22, v22
	v_max_f32_e32 v50, v38, v38
	v_max_f32_e32 v49, v50, v49
	v_max_f32_e32 v50, v23, v23
	v_max_f32_e32 v51, v39, v39
	v_max_f32_e32 v50, v51, v50
	v_max3_f32 v48, v48, v49, v50
	v_max_f32_e32 v49, v24, v24
	v_max_f32_e32 v50, v40, v40
	v_max_f32_e32 v49, v50, v49
	v_max_f32_e32 v50, v25, v25
	v_max_f32_e32 v51, v41, v41
	v_max_f32_e32 v50, v51, v50
	v_max3_f32 v48, v48, v49, v50
	v_max_f32_e32 v49, v26, v26
	v_max_f32_e32 v50, v42, v42
	v_max_f32_e32 v49, v50, v49
	v_max_f32_e32 v50, v27, v27
	v_max_f32_e32 v51, v43, v43
	v_max_f32_e32 v50, v51, v50
	v_max3_f32 v48, v48, v49, v50
	v_max_f32_e32 v49, v28, v28
	v_max_f32_e32 v50, v44, v44
	v_max_f32_e32 v49, v50, v49
	v_max_f32_e32 v50, v29, v29
	v_max_f32_e32 v51, v45, v45
	v_max_f32_e32 v50, v51, v50
	v_max3_f32 v48, v48, v49, v50
	v_max_f32_e32 v49, v30, v30
	v_max_f32_e32 v50, v46, v46
	v_max_f32_e32 v49, v50, v49
	v_max_f32_e32 v50, v31, v31
	v_max_f32_e32 v51, v47, v47
	v_max_f32_e32 v50, v51, v50
	v_max3_f32 v48, v48, v49, v50
	v_cndmask_b32_e32 v49, v219, v221, vcc
	v_lshlrev_b32_e32 v231, 2, v49
	ds_bpermute_b32 v49, v231, v48
	s_waitcnt lgkmcnt(0)
	v_max_f32_e32 v49, v49, v49
	v_max_f32_e32 v250, v48, v49
	v_sub_f32_e32 v32, v32, v250
	v_sub_f32_e32 v16, v16, v250
	v_exp_f32_e32 v80, v32
	v_sub_f32_e32 v32, v33, v250
	v_exp_f32_e32 v64, v16
	v_sub_f32_e32 v16, v17, v250
	v_exp_f32_e32 v81, v32
	v_sub_f32_e32 v32, v34, v250
	v_exp_f32_e32 v65, v16
	v_sub_f32_e32 v16, v18, v250
	v_exp_f32_e32 v82, v32
	v_sub_f32_e32 v32, v35, v250
	v_exp_f32_e32 v66, v16
	v_sub_f32_e32 v16, v19, v250
	v_exp_f32_e32 v83, v32
	v_sub_f32_e32 v32, v36, v250
	v_exp_f32_e32 v67, v16
	v_sub_f32_e32 v16, v20, v250
	v_exp_f32_e32 v84, v32
	v_sub_f32_e32 v32, v37, v250
	v_exp_f32_e32 v68, v16
	v_sub_f32_e32 v16, v21, v250
	v_exp_f32_e32 v85, v32
	v_sub_f32_e32 v32, v38, v250
	v_exp_f32_e32 v69, v16
	v_sub_f32_e32 v16, v22, v250
	v_exp_f32_e32 v86, v32
	v_sub_f32_e32 v32, v39, v250
	v_exp_f32_e32 v70, v16
	v_sub_f32_e32 v16, v23, v250
	v_exp_f32_e32 v87, v32
	v_sub_f32_e32 v32, v40, v250
	v_exp_f32_e32 v71, v16
	v_sub_f32_e32 v16, v24, v250
	v_exp_f32_e32 v88, v32
	v_sub_f32_e32 v32, v41, v250
	v_exp_f32_e32 v72, v16
	v_sub_f32_e32 v16, v25, v250
	v_exp_f32_e32 v89, v32
	v_sub_f32_e32 v32, v42, v250
	v_exp_f32_e32 v73, v16
	v_sub_f32_e32 v16, v26, v250
	v_exp_f32_e32 v90, v32
	v_sub_f32_e32 v32, v43, v250
	v_exp_f32_e32 v74, v16
	v_sub_f32_e32 v16, v27, v250
	v_exp_f32_e32 v91, v32
	v_sub_f32_e32 v32, v44, v250
	v_exp_f32_e32 v75, v16
	v_sub_f32_e32 v16, v28, v250
	v_exp_f32_e32 v92, v32
	v_sub_f32_e32 v32, v45, v250
	v_exp_f32_e32 v76, v16
	v_sub_f32_e32 v16, v29, v250
	v_exp_f32_e32 v93, v32
	v_sub_f32_e32 v32, v46, v250
	v_exp_f32_e32 v77, v16
	v_sub_f32_e32 v16, v30, v250
	v_exp_f32_e32 v94, v32
	v_sub_f32_e32 v32, v47, v250
	v_exp_f32_e32 v78, v16
	v_sub_f32_e32 v16, v31, v250
	v_exp_f32_e32 v95, v32
	v_exp_f32_e32 v79, v16
	v_lshlrev_b32_e32 v16, 2, v219
	v_and_or_b32 v236, v16, s4, v194
	v_mov_b64_e32 v[62:63], v[14:15]
	v_mov_b64_e32 v[30:31], v[14:15]
	v_mov_b64_e32 v[46:47], v[14:15]
	v_or_b32_e32 v237, 4, v236
	v_or_b32_e32 v238, 8, v236
	v_or_b32_e32 v239, 12, v236
	v_or_b32_e32 v240, 32, v236
	v_or_b32_e32 v241, 36, v236
	v_or_b32_e32 v242, 40, v236
	v_or_b32_e32 v194, 44, v236
	v_or_b32_e32 v243, 64, v236
	v_or_b32_e32 v233, 0x44, v236
	v_or_b32_e32 v244, 0x48, v236
	v_or_b32_e32 v234, 0x4c, v236
	v_or_b32_e32 v245, 0x60, v236
	v_or_b32_e32 v235, 0x64, v236
	v_or_b32_e32 v246, 0x68, v236
	v_or_b32_e32 v247, 0x6c, v236
	v_mov_b64_e32 v[60:61], v[12:13]
	v_mov_b64_e32 v[58:59], v[10:11]
	v_mov_b64_e32 v[56:57], v[8:9]
	v_mov_b64_e32 v[54:55], v[6:7]
	v_mov_b64_e32 v[52:53], v[4:5]
	v_mov_b64_e32 v[50:51], v[2:3]
	v_mov_b64_e32 v[48:49], v[0:1]
	v_mov_b64_e32 v[28:29], v[12:13]
	v_mov_b64_e32 v[26:27], v[10:11]
	v_mov_b64_e32 v[24:25], v[8:9]
	v_mov_b64_e32 v[22:23], v[6:7]
	v_mov_b64_e32 v[20:21], v[4:5]
	v_mov_b64_e32 v[18:19], v[2:3]
	v_mov_b64_e32 v[16:17], v[0:1]
	v_mov_b64_e32 v[44:45], v[12:13]
	v_mov_b64_e32 v[42:43], v[10:11]
	v_mov_b64_e32 v[40:41], v[8:9]
	v_mov_b64_e32 v[38:39], v[6:7]
	v_mov_b64_e32 v[36:37], v[4:5]
	v_mov_b64_e32 v[34:35], v[2:3]
	v_mov_b64_e32 v[32:33], v[0:1]
	.p2alignl 6, 3212836864

;     __device__ __forceinline__ size_t aoff(const Unit& u, size_t ts, int) const { return (size_t)u.pm * ts; }
;     __device__ __forceinline__ size_t boff(const Unit& u, size_t ts, int) const { return (size_t)u.pn * ts; }
;     __device__ __forceinline__ size_t aoff(const Unit& u, size_t ts, int K) const { return (size_t)(u.pm & 15) * ts + (size_t)(u.pm >> 4) * K * 2; }
;     __device__ __forceinline__ size_t boff(const Unit& u, size_t ts, int K) const { return (size_t)u.pn * ts + (size_t)(u.pm >> 4) * K * 2; }
; template <class Epi, class Sched, bool ALIGN_EPI = false, bool SP2 = false>
; __device__ __forceinline__ void gemm_phase(PG8_LAS unsigned char* lds, const Gemm g, const Sched& S, const Epi& E) {
;     ...
;         const bool has_next = S.next(ui + 1, nxt);
;         const char* nA = has_next ? (const char*)g.A + S.aoff(nxt, tstepA, K) : cA; const char* nB = has_next ? (const char*)g.Bt + S.boff(nxt, tstepB, K) : cB;
;         for (int t = 0; t < nt; t += 2) {
;             const bool last = (t == nt - 2);
;             const char* a1 = cA + (size_t)(t + 1) * kstep;
;             const char* a2 = last ? nA : cA + (size_t)(t + 2) * kstep; const char* b2 = last ? nB : cB + (size_t)(t + 2) * kstep;
;             const char* a3 = a2 + kstep; const char* b3 = b2 + kstep;
;     ...
;         for (int a = 0; a < 2; ++a)
; #pragma unroll
;             for (int b = 0; b < 2; ++b)
; #pragma unroll
;                 for (int m = 0; m < 4; ++m)
; #pragma unroll
;                     for (int n = 0; n < 2; ++n) acc[a][b][m][n] = (f32x4){0.f, 0.f, 0.f, 0.f};
;         cur = nxt; cA = nA; cB = nB; ++ui;
.LBB0_1216:
	s_ashr_i32 s69, s68, 31
	s_lshl_b64 s[52:53], s[68:69], s9
	s_add_u32 s76, s28, s52
	s_addc_u32 s77, s59, s53
	s_ashr_i32 s35, s34, 31
	s_lshl_b64 s[52:53], s[34:35], s9
	s_add_u32 s52, s47, s52
	v_mov_b32_e32 v123, 0
	s_addc_u32 s53, s29, s53
	s_andn2_b64 vcc, exec, s[88:89]
	v_mov_b32_e32 v122, v123
	v_mov_b32_e32 v121, v123
	v_mov_b32_e32 v120, v123
	v_mov_b32_e32 v127, v123
	v_mov_b32_e32 v126, v123
	v_mov_b32_e32 v125, v123
	v_mov_b32_e32 v124, v123
	v_mov_b32_e32 v111, v123
	v_mov_b32_e32 v110, v123
	v_mov_b32_e32 v109, v123
	v_mov_b32_e32 v108, v123
	v_mov_b32_e32 v107, v123
	v_mov_b32_e32 v106, v123
	v_mov_b32_e32 v105, v123
	v_mov_b32_e32 v104, v123
	v_mov_b32_e32 v95, v123
	v_mov_b32_e32 v94, v123
	v_mov_b32_e32 v93, v123
	v_mov_b32_e32 v92, v123
	v_mov_b32_e32 v91, v123
	v_mov_b32_e32 v90, v123
	v_mov_b32_e32 v89, v123
	v_mov_b32_e32 v88, v123
	v_mov_b32_e32 v79, v123
	v_mov_b32_e32 v78, v123
	v_mov_b32_e32 v77, v123
	v_mov_b32_e32 v76, v123
	v_mov_b32_e32 v75, v123
	v_mov_b32_e32 v74, v123
	v_mov_b32_e32 v73, v123
	v_mov_b32_e32 v72, v123
	v_mov_b32_e32 v119, v123
	v_mov_b32_e32 v118, v123
	v_mov_b32_e32 v117, v123
	v_mov_b32_e32 v116, v123
	v_mov_b32_e32 v115, v123
	v_mov_b32_e32 v114, v123
	v_mov_b32_e32 v113, v123
	v_mov_b32_e32 v112, v123
	v_mov_b32_e32 v103, v123
	v_mov_b32_e32 v102, v123
	v_mov_b32_e32 v101, v123
	v_mov_b32_e32 v100, v123
	v_mov_b32_e32 v99, v123
	v_mov_b32_e32 v98, v123
	v_mov_b32_e32 v97, v123
	v_mov_b32_e32 v96, v123
	v_mov_b32_e32 v87, v123
	v_mov_b32_e32 v86, v123
	v_mov_b32_e32 v85, v123
	v_mov_b32_e32 v84, v123
	v_mov_b32_e32 v83, v123
	v_mov_b32_e32 v82, v123
	v_mov_b32_e32 v81, v123
	v_mov_b32_e32 v80, v123
	v_mov_b32_e32 v71, v123
	v_mov_b32_e32 v70, v123
	v_mov_b32_e32 v69, v123
	v_mov_b32_e32 v68, v123
	v_mov_b32_e32 v67, v123
	v_mov_b32_e32 v66, v123
	v_mov_b32_e32 v65, v123
	v_mov_b32_e32 v64, v123
	v_mov_b32_e32 v63, v123
	v_mov_b32_e32 v62, v123
	v_mov_b32_e32 v61, v123
	v_mov_b32_e32 v60, v123
	v_mov_b32_e32 v59, v123
	v_mov_b32_e32 v58, v123
	v_mov_b32_e32 v57, v123
	v_mov_b32_e32 v56, v123
	v_mov_b32_e32 v47, v123
	v_mov_b32_e32 v46, v123
	v_mov_b32_e32 v45, v123
	v_mov_b32_e32 v44, v123
	v_mov_b32_e32 v43, v123
	v_mov_b32_e32 v42, v123
	v_mov_b32_e32 v41, v123
	v_mov_b32_e32 v40, v123
	v_mov_b32_e32 v31, v123
	v_mov_b32_e32 v30, v123
	v_mov_b32_e32 v29, v123
	v_mov_b32_e32 v28, v123
	v_mov_b32_e32 v27, v123
	v_mov_b32_e32 v26, v123
	v_mov_b32_e32 v25, v123
	v_mov_b32_e32 v24, v123
	v_mov_b32_e32 v15, v123
	v_mov_b32_e32 v14, v123
	v_mov_b32_e32 v13, v123
	v_mov_b32_e32 v12, v123
	v_mov_b32_e32 v11, v123
	v_mov_b32_e32 v10, v123
	v_mov_b32_e32 v9, v123
	v_mov_b32_e32 v8, v123
	v_mov_b32_e32 v55, v123
	v_mov_b32_e32 v54, v123
	v_mov_b32_e32 v53, v123
	v_mov_b32_e32 v52, v123
	v_mov_b32_e32 v51, v123
	v_mov_b32_e32 v50, v123
	v_mov_b32_e32 v49, v123
	v_mov_b32_e32 v48, v123
	v_mov_b32_e32 v39, v123
	v_mov_b32_e32 v38, v123
	v_mov_b32_e32 v37, v123
	v_mov_b32_e32 v36, v123
	v_mov_b32_e32 v35, v123
	v_mov_b32_e32 v34, v123
	v_mov_b32_e32 v33, v123
	v_mov_b32_e32 v32, v123
	v_mov_b32_e32 v23, v123
	v_mov_b32_e32 v22, v123
	v_mov_b32_e32 v21, v123
	v_mov_b32_e32 v20, v123
	v_mov_b32_e32 v19, v123
	v_mov_b32_e32 v18, v123
	v_mov_b32_e32 v17, v123
	v_mov_b32_e32 v16, v123
	v_mov_b32_e32 v7, v123
	v_mov_b32_e32 v6, v123
	v_mov_b32_e32 v5, v123
	v_mov_b32_e32 v4, v123
	v_mov_b32_e32 v3, v123
	v_mov_b32_e32 v2, v123
	v_mov_b32_e32 v1, v123
	v_mov_b32_e32 v0, v123
	s_cbranch_vccnz .LBB0_1219
	s_and_b64 s[62:63], s[38:39], exec
	s_cselect_b32 s35, s77, s43
	s_cselect_b32 s41, s76, s42
	s_cselect_b32 s61, s53, s45
	s_cselect_b32 s62, s52, s44
	s_add_u32 s42, s42, 0x80
	s_addc_u32 s43, s43, 0
	s_add_u32 s63, s44, 0x100
	v_mov_b32_e32 v0, 0
	s_addc_u32 s69, s45, 0
	s_mov_b32 s44, 0
	v_mov_b32_e32 v1, v0
	v_mov_b32_e32 v2, v0
	v_mov_b32_e32 v3, v0
	v_mov_b32_e32 v4, v0
	v_mov_b32_e32 v5, v0
	v_mov_b32_e32 v6, v0
	v_mov_b32_e32 v7, v0
	v_mov_b32_e32 v16, v0
	v_mov_b32_e32 v17, v0
	v_mov_b32_e32 v18, v0
	v_mov_b32_e32 v19, v0
	v_mov_b32_e32 v20, v0
	v_mov_b32_e32 v21, v0
	v_mov_b32_e32 v22, v0
	v_mov_b32_e32 v23, v0
	v_mov_b32_e32 v32, v0
	v_mov_b32_e32 v33, v0
	v_mov_b32_e32 v34, v0
	v_mov_b32_e32 v35, v0
	v_mov_b32_e32 v36, v0
	v_mov_b32_e32 v37, v0
	v_mov_b32_e32 v38, v0
	v_mov_b32_e32 v39, v0
	v_mov_b32_e32 v48, v0
	v_mov_b32_e32 v49, v0
	v_mov_b32_e32 v50, v0
	v_mov_b32_e32 v51, v0
	v_mov_b32_e32 v52, v0
	v_mov_b32_e32 v53, v0
	v_mov_b32_e32 v54, v0
	v_mov_b32_e32 v55, v0
	v_mov_b32_e32 v8, v0
	v_mov_b32_e32 v9, v0
	v_mov_b32_e32 v10, v0
	v_mov_b32_e32 v11, v0
	v_mov_b32_e32 v12, v0
	v_mov_b32_e32 v13, v0
	v_mov_b32_e32 v14, v0
	v_mov_b32_e32 v15, v0
	v_mov_b32_e32 v24, v0
	v_mov_b32_e32 v25, v0
	v_mov_b32_e32 v26, v0
	v_mov_b32_e32 v27, v0
	v_mov_b32_e32 v28, v0
	v_mov_b32_e32 v29, v0
	v_mov_b32_e32 v30, v0
	v_mov_b32_e32 v31, v0
	v_mov_b32_e32 v40, v0
	v_mov_b32_e32 v41, v0
	v_mov_b32_e32 v42, v0
	v_mov_b32_e32 v43, v0
	v_mov_b32_e32 v44, v0
	v_mov_b32_e32 v45, v0
	v_mov_b32_e32 v46, v0
	v_mov_b32_e32 v47, v0
	v_mov_b32_e32 v56, v0
	v_mov_b32_e32 v57, v0
	v_mov_b32_e32 v58, v0
	v_mov_b32_e32 v59, v0
	v_mov_b32_e32 v60, v0
	v_mov_b32_e32 v61, v0
	v_mov_b32_e32 v62, v0
	v_mov_b32_e32 v63, v0
	v_mov_b32_e32 v64, v0
	v_mov_b32_e32 v65, v0
	v_mov_b32_e32 v66, v0
	v_mov_b32_e32 v67, v0
	v_mov_b32_e32 v68, v0
	v_mov_b32_e32 v69, v0
	v_mov_b32_e32 v70, v0
	v_mov_b32_e32 v71, v0
	v_mov_b32_e32 v80, v0
	v_mov_b32_e32 v81, v0
	v_mov_b32_e32 v82, v0
	v_mov_b32_e32 v83, v0
	v_mov_b32_e32 v84, v0
	v_mov_b32_e32 v85, v0
	v_mov_b32_e32 v86, v0
	v_mov_b32_e32 v87, v0
	v_mov_b32_e32 v96, v0
	v_mov_b32_e32 v97, v0
	v_mov_b32_e32 v98, v0
	v_mov_b32_e32 v99, v0
	v_mov_b32_e32 v100, v0
	v_mov_b32_e32 v101, v0
	v_mov_b32_e32 v102, v0
	v_mov_b32_e32 v103, v0
	v_mov_b32_e32 v112, v0
	v_mov_b32_e32 v113, v0
	v_mov_b32_e32 v114, v0
	v_mov_b32_e32 v115, v0
	v_mov_b32_e32 v116, v0
	v_mov_b32_e32 v117, v0
	v_mov_b32_e32 v118, v0
	v_mov_b32_e32 v119, v0
	v_mov_b32_e32 v72, v0
	v_mov_b32_e32 v73, v0
	v_mov_b32_e32 v74, v0
	v_mov_b32_e32 v75, v0
	v_mov_b32_e32 v76, v0
	v_mov_b32_e32 v77, v0
	v_mov_b32_e32 v78, v0
	v_mov_b32_e32 v79, v0
	v_mov_b32_e32 v88, v0
	v_mov_b32_e32 v89, v0
	v_mov_b32_e32 v90, v0
	v_mov_b32_e32 v91, v0
	v_mov_b32_e32 v92, v0
	v_mov_b32_e32 v93, v0
	v_mov_b32_e32 v94, v0
	v_mov_b32_e32 v95, v0
	v_mov_b32_e32 v104, v0
	v_mov_b32_e32 v105, v0
	v_mov_b32_e32 v106, v0
	v_mov_b32_e32 v107, v0
	v_mov_b32_e32 v108, v0
	v_mov_b32_e32 v109, v0
	v_mov_b32_e32 v110, v0
	v_mov_b32_e32 v111, v0
	v_mov_b32_e32 v124, v0
	v_mov_b32_e32 v125, v0
	v_mov_b32_e32 v126, v0
	v_mov_b32_e32 v127, v0
	v_mov_b32_e32 v120, v0
	v_mov_b32_e32 v121, v0
	v_mov_b32_e32 v122, v0
	v_mov_b32_e32 v123, v0
	.p2alignl 6, 3212836864

; template <class Epi, class Sched, bool ALIGN_EPI = false, bool SP2 = false>
; __device__ __forceinline__ void gemm_phase(PG8_LAS unsigned char* lds, const Gemm g, const Sched& S, const Epi& E) {
;     ...
;         for (int t = 0; t < nt; t += 2) {
;             const bool last = (t == nt - 2);
;             const char* a1 = cA + (size_t)(t + 1) * kstep;
;             const char* a2 = last ? nA : cA + (size_t)(t + 2) * kstep; const char* b2 = last ? nB : cB + (size_t)(t + 2) * kstep;
;             const char* a3 = a2 + kstep; const char* b3 = b2 + kstep;
;     ...
;         for (int a = 0; a < 2; ++a)
; #pragma unroll
;             for (int b = 0; b < 2; ++b)
; #pragma unroll
;                 for (int m = 0; m < 4; ++m)
; #pragma unroll
;                     for (int n = 0; n < 2; ++n) acc[a][b][m][n] = (f32x4){0.f, 0.f, 0.f, 0.f};
;         cur = nxt; cA = nA; cB = nB; ++ui;
.LBB0_1461:
	v_mov_b32_e32 v127, 0
	s_andn2_b64 vcc, exec, s[46:47]
	v_mov_b32_e32 v126, v127
	v_mov_b32_e32 v125, v127
	v_mov_b32_e32 v124, v127
	v_mov_b32_e32 v123, v127
	v_mov_b32_e32 v122, v127
	v_mov_b32_e32 v121, v127
	v_mov_b32_e32 v120, v127
	v_mov_b32_e32 v119, v127
	v_mov_b32_e32 v118, v127
	v_mov_b32_e32 v117, v127
	v_mov_b32_e32 v116, v127
	v_mov_b32_e32 v115, v127
	v_mov_b32_e32 v114, v127
	v_mov_b32_e32 v113, v127
	v_mov_b32_e32 v112, v127
	v_mov_b32_e32 v111, v127
	v_mov_b32_e32 v110, v127
	v_mov_b32_e32 v109, v127
	v_mov_b32_e32 v108, v127
	v_mov_b32_e32 v107, v127
	v_mov_b32_e32 v106, v127
	v_mov_b32_e32 v105, v127
	v_mov_b32_e32 v104, v127
	v_mov_b32_e32 v103, v127
	v_mov_b32_e32 v102, v127
	v_mov_b32_e32 v101, v127
	v_mov_b32_e32 v100, v127
	v_mov_b32_e32 v99, v127
	v_mov_b32_e32 v98, v127
	v_mov_b32_e32 v97, v127
	v_mov_b32_e32 v96, v127
	v_mov_b32_e32 v63, v127
	v_mov_b32_e32 v62, v127
	v_mov_b32_e32 v61, v127
	v_mov_b32_e32 v60, v127
	v_mov_b32_e32 v59, v127
	v_mov_b32_e32 v58, v127
	v_mov_b32_e32 v57, v127
	v_mov_b32_e32 v56, v127
	v_mov_b32_e32 v55, v127
	v_mov_b32_e32 v54, v127
	v_mov_b32_e32 v53, v127
	v_mov_b32_e32 v52, v127
	v_mov_b32_e32 v51, v127
	v_mov_b32_e32 v50, v127
	v_mov_b32_e32 v49, v127
	v_mov_b32_e32 v48, v127
	v_mov_b32_e32 v47, v127
	v_mov_b32_e32 v46, v127
	v_mov_b32_e32 v45, v127
	v_mov_b32_e32 v44, v127
	v_mov_b32_e32 v43, v127
	v_mov_b32_e32 v42, v127
	v_mov_b32_e32 v41, v127
	v_mov_b32_e32 v40, v127
	v_mov_b32_e32 v39, v127
	v_mov_b32_e32 v38, v127
	v_mov_b32_e32 v37, v127
	v_mov_b32_e32 v36, v127
	v_mov_b32_e32 v35, v127
	v_mov_b32_e32 v34, v127
	v_mov_b32_e32 v33, v127
	v_mov_b32_e32 v32, v127
	v_mov_b32_e32 v95, v127
	v_mov_b32_e32 v94, v127
	v_mov_b32_e32 v93, v127
	v_mov_b32_e32 v92, v127
	v_mov_b32_e32 v91, v127
	v_mov_b32_e32 v90, v127
	v_mov_b32_e32 v89, v127
	v_mov_b32_e32 v88, v127
	v_mov_b32_e32 v87, v127
	v_mov_b32_e32 v86, v127
	v_mov_b32_e32 v85, v127
	v_mov_b32_e32 v84, v127
	v_mov_b32_e32 v83, v127
	v_mov_b32_e32 v82, v127
	v_mov_b32_e32 v81, v127
	v_mov_b32_e32 v80, v127
	v_mov_b32_e32 v79, v127
	v_mov_b32_e32 v78, v127
	v_mov_b32_e32 v77, v127
	v_mov_b32_e32 v76, v127
	v_mov_b32_e32 v75, v127
	v_mov_b32_e32 v74, v127
	v_mov_b32_e32 v73, v127
	v_mov_b32_e32 v72, v127
	v_mov_b32_e32 v71, v127
	v_mov_b32_e32 v70, v127
	v_mov_b32_e32 v69, v127
	v_mov_b32_e32 v68, v127
	v_mov_b32_e32 v67, v127
	v_mov_b32_e32 v66, v127
	v_mov_b32_e32 v65, v127
	v_mov_b32_e32 v64, v127
	v_mov_b32_e32 v31, v127
	v_mov_b32_e32 v30, v127
	v_mov_b32_e32 v29, v127
	v_mov_b32_e32 v28, v127
	v_mov_b32_e32 v27, v127
	v_mov_b32_e32 v26, v127
	v_mov_b32_e32 v25, v127
	v_mov_b32_e32 v24, v127
	v_mov_b32_e32 v23, v127
	v_mov_b32_e32 v22, v127
	v_mov_b32_e32 v21, v127
	v_mov_b32_e32 v20, v127
	v_mov_b32_e32 v19, v127
	v_mov_b32_e32 v18, v127
	v_mov_b32_e32 v17, v127
	v_mov_b32_e32 v16, v127
	v_mov_b32_e32 v15, v127
	v_mov_b32_e32 v14, v127
	v_mov_b32_e32 v13, v127
	v_mov_b32_e32 v12, v127
	v_mov_b32_e32 v11, v127
	v_mov_b32_e32 v10, v127
	v_mov_b32_e32 v9, v127
	v_mov_b32_e32 v8, v127
	v_mov_b32_e32 v7, v127
	v_mov_b32_e32 v6, v127
	v_mov_b32_e32 v5, v127
	v_mov_b32_e32 v4, v127
	v_mov_b32_e32 v3, v127
	v_mov_b32_e32 v2, v127
	v_mov_b32_e32 v1, v127
	v_mov_b32_e32 v0, v127
	s_cbranch_vccnz .LBB0_1464
	s_add_u32 s40, s86, 0x80
	s_addc_u32 s41, s87, 0
	s_add_u32 s78, s84, 0x100
	v_mov_b32_e32 v0, 0
	s_addc_u32 s79, s85, 0
	s_mov_b32 s84, 0
	v_mov_b32_e32 v1, v0
	v_mov_b32_e32 v2, v0
	v_mov_b32_e32 v3, v0
	v_mov_b32_e32 v4, v0
	v_mov_b32_e32 v5, v0
	v_mov_b32_e32 v6, v0
	v_mov_b32_e32 v7, v0
	v_mov_b32_e32 v8, v0
	v_mov_b32_e32 v9, v0
	v_mov_b32_e32 v10, v0
	v_mov_b32_e32 v11, v0
	v_mov_b32_e32 v12, v0
	v_mov_b32_e32 v13, v0
	v_mov_b32_e32 v14, v0
	v_mov_b32_e32 v15, v0
	v_mov_b32_e32 v16, v0
	v_mov_b32_e32 v17, v0
	v_mov_b32_e32 v18, v0
	v_mov_b32_e32 v19, v0
	v_mov_b32_e32 v20, v0
	v_mov_b32_e32 v21, v0
	v_mov_b32_e32 v22, v0
	v_mov_b32_e32 v23, v0
	v_mov_b32_e32 v24, v0
	v_mov_b32_e32 v25, v0
	v_mov_b32_e32 v26, v0
	v_mov_b32_e32 v27, v0
	v_mov_b32_e32 v28, v0
	v_mov_b32_e32 v29, v0
	v_mov_b32_e32 v30, v0
	v_mov_b32_e32 v31, v0
	v_mov_b32_e32 v64, v0
	v_mov_b32_e32 v65, v0
	v_mov_b32_e32 v66, v0
	v_mov_b32_e32 v67, v0
	v_mov_b32_e32 v68, v0
	v_mov_b32_e32 v69, v0
	v_mov_b32_e32 v70, v0
	v_mov_b32_e32 v71, v0
	v_mov_b32_e32 v72, v0
	v_mov_b32_e32 v73, v0
	v_mov_b32_e32 v74, v0
	v_mov_b32_e32 v75, v0
	v_mov_b32_e32 v76, v0
	v_mov_b32_e32 v77, v0
	v_mov_b32_e32 v78, v0
	v_mov_b32_e32 v79, v0
	v_mov_b32_e32 v80, v0
	v_mov_b32_e32 v81, v0
	v_mov_b32_e32 v82, v0
	v_mov_b32_e32 v83, v0
	v_mov_b32_e32 v84, v0
	v_mov_b32_e32 v85, v0
	v_mov_b32_e32 v86, v0
	v_mov_b32_e32 v87, v0
	v_mov_b32_e32 v88, v0
	v_mov_b32_e32 v89, v0
	v_mov_b32_e32 v90, v0
	v_mov_b32_e32 v91, v0
	v_mov_b32_e32 v92, v0
	v_mov_b32_e32 v93, v0
	v_mov_b32_e32 v94, v0
	v_mov_b32_e32 v95, v0
	v_mov_b32_e32 v32, v0
	v_mov_b32_e32 v33, v0
	v_mov_b32_e32 v34, v0
	v_mov_b32_e32 v35, v0
	v_mov_b32_e32 v36, v0
	v_mov_b32_e32 v37, v0
	v_mov_b32_e32 v38, v0
	v_mov_b32_e32 v39, v0
	v_mov_b32_e32 v40, v0
	v_mov_b32_e32 v41, v0
	v_mov_b32_e32 v42, v0
	v_mov_b32_e32 v43, v0
	v_mov_b32_e32 v44, v0
	v_mov_b32_e32 v45, v0
	v_mov_b32_e32 v46, v0
	v_mov_b32_e32 v47, v0
	v_mov_b32_e32 v48, v0
	v_mov_b32_e32 v49, v0
	v_mov_b32_e32 v50, v0
	v_mov_b32_e32 v51, v0
	v_mov_b32_e32 v52, v0
	v_mov_b32_e32 v53, v0
	v_mov_b32_e32 v54, v0
	v_mov_b32_e32 v55, v0
	v_mov_b32_e32 v56, v0
	v_mov_b32_e32 v57, v0
	v_mov_b32_e32 v58, v0
	v_mov_b32_e32 v59, v0
	v_mov_b32_e32 v60, v0
	v_mov_b32_e32 v61, v0
	v_mov_b32_e32 v62, v0
	v_mov_b32_e32 v63, v0
	v_mov_b32_e32 v96, v0
	v_mov_b32_e32 v97, v0
	v_mov_b32_e32 v98, v0
	v_mov_b32_e32 v99, v0
	v_mov_b32_e32 v100, v0
	v_mov_b32_e32 v101, v0
	v_mov_b32_e32 v102, v0
	v_mov_b32_e32 v103, v0
	v_mov_b32_e32 v104, v0
	v_mov_b32_e32 v105, v0
	v_mov_b32_e32 v106, v0
	v_mov_b32_e32 v107, v0
	v_mov_b32_e32 v108, v0
	v_mov_b32_e32 v109, v0
	v_mov_b32_e32 v110, v0
	v_mov_b32_e32 v111, v0
	v_mov_b32_e32 v112, v0
	v_mov_b32_e32 v113, v0
	v_mov_b32_e32 v114, v0
	v_mov_b32_e32 v115, v0
	v_mov_b32_e32 v116, v0
	v_mov_b32_e32 v117, v0
	v_mov_b32_e32 v118, v0
	v_mov_b32_e32 v119, v0
	v_mov_b32_e32 v120, v0
	v_mov_b32_e32 v121, v0
	v_mov_b32_e32 v122, v0
	v_mov_b32_e32 v123, v0
	v_mov_b32_e32 v124, v0
	v_mov_b32_e32 v125, v0
	v_mov_b32_e32 v126, v0
	v_mov_b32_e32 v127, v0
	.p2alignl 6, 3212836864

; template <class Epi, class Sched, bool ALIGN_EPI = false, bool SP2 = false>
; __device__ __forceinline__ void gemm_phase(PG8_LAS unsigned char* lds, const Gemm g, const Sched& S, const Epi& E) {
;     ...
;         for (int t = 0; t < nt; t += 2) {
;             const bool last = (t == nt - 2);
;             const char* a1 = cA + (size_t)(t + 1) * kstep;
;             const char* a2 = last ? nA : cA + (size_t)(t + 2) * kstep; const char* b2 = last ? nB : cB + (size_t)(t + 2) * kstep;
;             const char* a3 = a2 + kstep; const char* b3 = b2 + kstep;
;     ...
;         for (int a = 0; a < 2; ++a)
; #pragma unroll
;             for (int b = 0; b < 2; ++b)
; #pragma unroll
;                 for (int m = 0; m < 4; ++m)
; #pragma unroll
;                     for (int n = 0; n < 2; ++n) acc[a][b][m][n] = (f32x4){0.f, 0.f, 0.f, 0.f};
;         cur = nxt; cA = nA; cB = nB; ++ui;
.LBB0_1491:
	v_mov_b32_e32 v127, 0
	s_andn2_b64 vcc, exec, s[34:35]
	v_mov_b32_e32 v126, v127
	v_mov_b32_e32 v125, v127
	v_mov_b32_e32 v124, v127
	v_mov_b32_e32 v123, v127
	v_mov_b32_e32 v122, v127
	v_mov_b32_e32 v121, v127
	v_mov_b32_e32 v120, v127
	v_mov_b32_e32 v119, v127
	v_mov_b32_e32 v118, v127
	v_mov_b32_e32 v117, v127
	v_mov_b32_e32 v116, v127
	v_mov_b32_e32 v115, v127
	v_mov_b32_e32 v114, v127
	v_mov_b32_e32 v113, v127
	v_mov_b32_e32 v112, v127
	v_mov_b32_e32 v111, v127
	v_mov_b32_e32 v110, v127
	v_mov_b32_e32 v109, v127
	v_mov_b32_e32 v108, v127
	v_mov_b32_e32 v107, v127
	v_mov_b32_e32 v106, v127
	v_mov_b32_e32 v105, v127
	v_mov_b32_e32 v104, v127
	v_mov_b32_e32 v103, v127
	v_mov_b32_e32 v102, v127
	v_mov_b32_e32 v101, v127
	v_mov_b32_e32 v100, v127
	v_mov_b32_e32 v99, v127
	v_mov_b32_e32 v98, v127
	v_mov_b32_e32 v97, v127
	v_mov_b32_e32 v96, v127
	v_mov_b32_e32 v63, v127
	v_mov_b32_e32 v62, v127
	v_mov_b32_e32 v61, v127
	v_mov_b32_e32 v60, v127
	v_mov_b32_e32 v59, v127
	v_mov_b32_e32 v58, v127
	v_mov_b32_e32 v57, v127
	v_mov_b32_e32 v56, v127
	v_mov_b32_e32 v55, v127
	v_mov_b32_e32 v54, v127
	v_mov_b32_e32 v53, v127
	v_mov_b32_e32 v52, v127
	v_mov_b32_e32 v51, v127
	v_mov_b32_e32 v50, v127
	v_mov_b32_e32 v49, v127
	v_mov_b32_e32 v48, v127
	v_mov_b32_e32 v47, v127
	v_mov_b32_e32 v46, v127
	v_mov_b32_e32 v45, v127
	v_mov_b32_e32 v44, v127
	v_mov_b32_e32 v43, v127
	v_mov_b32_e32 v42, v127
	v_mov_b32_e32 v41, v127
	v_mov_b32_e32 v40, v127
	v_mov_b32_e32 v39, v127
	v_mov_b32_e32 v38, v127
	v_mov_b32_e32 v37, v127
	v_mov_b32_e32 v36, v127
	v_mov_b32_e32 v35, v127
	v_mov_b32_e32 v34, v127
	v_mov_b32_e32 v33, v127
	v_mov_b32_e32 v32, v127
	v_mov_b32_e32 v95, v127
	v_mov_b32_e32 v94, v127
	v_mov_b32_e32 v93, v127
	v_mov_b32_e32 v92, v127
	v_mov_b32_e32 v91, v127
	v_mov_b32_e32 v90, v127
	v_mov_b32_e32 v89, v127
	v_mov_b32_e32 v88, v127
	v_mov_b32_e32 v87, v127
	v_mov_b32_e32 v86, v127
	v_mov_b32_e32 v85, v127
	v_mov_b32_e32 v84, v127
	v_mov_b32_e32 v83, v127
	v_mov_b32_e32 v82, v127
	v_mov_b32_e32 v81, v127
	v_mov_b32_e32 v80, v127
	v_mov_b32_e32 v79, v127
	v_mov_b32_e32 v78, v127
	v_mov_b32_e32 v77, v127
	v_mov_b32_e32 v76, v127
	v_mov_b32_e32 v75, v127
	v_mov_b32_e32 v74, v127
	v_mov_b32_e32 v73, v127
	v_mov_b32_e32 v72, v127
	v_mov_b32_e32 v71, v127
	v_mov_b32_e32 v70, v127
	v_mov_b32_e32 v69, v127
	v_mov_b32_e32 v68, v127
	v_mov_b32_e32 v67, v127
	v_mov_b32_e32 v66, v127
	v_mov_b32_e32 v65, v127
	v_mov_b32_e32 v64, v127
	v_mov_b32_e32 v31, v127
	v_mov_b32_e32 v30, v127
	v_mov_b32_e32 v29, v127
	v_mov_b32_e32 v28, v127
	v_mov_b32_e32 v27, v127
	v_mov_b32_e32 v26, v127
	v_mov_b32_e32 v25, v127
	v_mov_b32_e32 v24, v127
	v_mov_b32_e32 v23, v127
	v_mov_b32_e32 v22, v127
	v_mov_b32_e32 v21, v127
	v_mov_b32_e32 v20, v127
	v_mov_b32_e32 v19, v127
	v_mov_b32_e32 v18, v127
	v_mov_b32_e32 v17, v127
	v_mov_b32_e32 v16, v127
	v_mov_b32_e32 v15, v127
	v_mov_b32_e32 v14, v127
	v_mov_b32_e32 v13, v127
	v_mov_b32_e32 v12, v127
	v_mov_b32_e32 v11, v127
	v_mov_b32_e32 v10, v127
	v_mov_b32_e32 v9, v127
	v_mov_b32_e32 v8, v127
	v_mov_b32_e32 v7, v127
	v_mov_b32_e32 v6, v127
	v_mov_b32_e32 v5, v127
	v_mov_b32_e32 v4, v127
	v_mov_b32_e32 v3, v127
	v_mov_b32_e32 v2, v127
	v_mov_b32_e32 v1, v127
	v_mov_b32_e32 v0, v127
	s_cbranch_vccnz .LBB0_1494
	s_add_u32 s84, s84, 0x80
	s_addc_u32 s85, s85, 0
	s_add_u32 s64, s86, 0x100
	v_mov_b32_e32 v0, 0
	s_addc_u32 s78, s87, 0
	s_mov_b32 s79, 0
	v_mov_b32_e32 v1, v0
	v_mov_b32_e32 v2, v0
	v_mov_b32_e32 v3, v0
	v_mov_b32_e32 v4, v0
	v_mov_b32_e32 v5, v0
	v_mov_b32_e32 v6, v0
	v_mov_b32_e32 v7, v0
	v_mov_b32_e32 v8, v0
	v_mov_b32_e32 v9, v0
	v_mov_b32_e32 v10, v0
	v_mov_b32_e32 v11, v0
	v_mov_b32_e32 v12, v0
	v_mov_b32_e32 v13, v0
	v_mov_b32_e32 v14, v0
	v_mov_b32_e32 v15, v0
	v_mov_b32_e32 v16, v0
	v_mov_b32_e32 v17, v0
	v_mov_b32_e32 v18, v0
	v_mov_b32_e32 v19, v0
	v_mov_b32_e32 v20, v0
	v_mov_b32_e32 v21, v0
	v_mov_b32_e32 v22, v0
	v_mov_b32_e32 v23, v0
	v_mov_b32_e32 v24, v0
	v_mov_b32_e32 v25, v0
	v_mov_b32_e32 v26, v0
	v_mov_b32_e32 v27, v0
	v_mov_b32_e32 v28, v0
	v_mov_b32_e32 v29, v0
	v_mov_b32_e32 v30, v0
	v_mov_b32_e32 v31, v0
	v_mov_b32_e32 v64, v0
	v_mov_b32_e32 v65, v0
	v_mov_b32_e32 v66, v0
	v_mov_b32_e32 v67, v0
	v_mov_b32_e32 v68, v0
	v_mov_b32_e32 v69, v0
	v_mov_b32_e32 v70, v0
	v_mov_b32_e32 v71, v0
	v_mov_b32_e32 v72, v0
	v_mov_b32_e32 v73, v0
	v_mov_b32_e32 v74, v0
	v_mov_b32_e32 v75, v0
	v_mov_b32_e32 v76, v0
	v_mov_b32_e32 v77, v0
	v_mov_b32_e32 v78, v0
	v_mov_b32_e32 v79, v0
	v_mov_b32_e32 v80, v0
	v_mov_b32_e32 v81, v0
	v_mov_b32_e32 v82, v0
	v_mov_b32_e32 v83, v0
	v_mov_b32_e32 v84, v0
	v_mov_b32_e32 v85, v0
	v_mov_b32_e32 v86, v0
	v_mov_b32_e32 v87, v0
	v_mov_b32_e32 v88, v0
	v_mov_b32_e32 v89, v0
	v_mov_b32_e32 v90, v0
	v_mov_b32_e32 v91, v0
	v_mov_b32_e32 v92, v0
	v_mov_b32_e32 v93, v0
	v_mov_b32_e32 v94, v0
	v_mov_b32_e32 v95, v0
	v_mov_b32_e32 v32, v0
	v_mov_b32_e32 v33, v0
	v_mov_b32_e32 v34, v0
	v_mov_b32_e32 v35, v0
	v_mov_b32_e32 v36, v0
	v_mov_b32_e32 v37, v0
	v_mov_b32_e32 v38, v0
	v_mov_b32_e32 v39, v0
	v_mov_b32_e32 v40, v0
	v_mov_b32_e32 v41, v0
	v_mov_b32_e32 v42, v0
	v_mov_b32_e32 v43, v0
	v_mov_b32_e32 v44, v0
	v_mov_b32_e32 v45, v0
	v_mov_b32_e32 v46, v0
	v_mov_b32_e32 v47, v0
	v_mov_b32_e32 v48, v0
	v_mov_b32_e32 v49, v0
	v_mov_b32_e32 v50, v0
	v_mov_b32_e32 v51, v0
	v_mov_b32_e32 v52, v0
	v_mov_b32_e32 v53, v0
	v_mov_b32_e32 v54, v0
	v_mov_b32_e32 v55, v0
	v_mov_b32_e32 v56, v0
	v_mov_b32_e32 v57, v0
	v_mov_b32_e32 v58, v0
	v_mov_b32_e32 v59, v0
	v_mov_b32_e32 v60, v0
	v_mov_b32_e32 v61, v0
	v_mov_b32_e32 v62, v0
	v_mov_b32_e32 v63, v0
	v_mov_b32_e32 v96, v0
	v_mov_b32_e32 v97, v0
	v_mov_b32_e32 v98, v0
	v_mov_b32_e32 v99, v0
	v_mov_b32_e32 v100, v0
	v_mov_b32_e32 v101, v0
	v_mov_b32_e32 v102, v0
	v_mov_b32_e32 v103, v0
	v_mov_b32_e32 v104, v0
	v_mov_b32_e32 v105, v0
	v_mov_b32_e32 v106, v0
	v_mov_b32_e32 v107, v0
	v_mov_b32_e32 v108, v0
	v_mov_b32_e32 v109, v0
	v_mov_b32_e32 v110, v0
	v_mov_b32_e32 v111, v0
	v_mov_b32_e32 v112, v0
	v_mov_b32_e32 v113, v0
	v_mov_b32_e32 v114, v0
	v_mov_b32_e32 v115, v0
	v_mov_b32_e32 v116, v0
	v_mov_b32_e32 v117, v0
	v_mov_b32_e32 v118, v0
	v_mov_b32_e32 v119, v0
	v_mov_b32_e32 v120, v0
	v_mov_b32_e32 v121, v0
	v_mov_b32_e32 v122, v0
	v_mov_b32_e32 v123, v0
	v_mov_b32_e32 v124, v0
	v_mov_b32_e32 v125, v0
	v_mov_b32_e32 v126, v0
	v_mov_b32_e32 v127, v0
	.p2alignl 6, 3212836864

;     __device__ __forceinline__ size_t aoff(const Unit& u, size_t ts, int) const { return (size_t)u.pm * ts; }
;     __device__ __forceinline__ size_t boff(const Unit& u, size_t ts, int) const { return (size_t)u.pn * ts; }
;     __device__ __forceinline__ size_t aoff(const Unit& u, size_t ts, int K) const { return (size_t)(u.pm & 15) * ts + (size_t)(u.pm >> 4) * K * 2; }
;     __device__ __forceinline__ size_t boff(const Unit& u, size_t ts, int K) const { return (size_t)u.pn * ts + (size_t)(u.pm >> 4) * K * 2; }
; template <class Epi, class Sched, bool ALIGN_EPI = false, bool SP2 = false>
; __device__ __forceinline__ void gemm_phase(PG8_LAS unsigned char* lds, const Gemm g, const Sched& S, const Epi& E) {
;     ...
;         const bool has_next = S.next(ui + 1, nxt);
;         const char* nA = has_next ? (const char*)g.A + S.aoff(nxt, tstepA, K) : cA; const char* nB = has_next ? (const char*)g.Bt + S.boff(nxt, tstepB, K) : cB;
;         for (int t = 0; t < nt; t += 2) {
;             const bool last = (t == nt - 2);
;             const char* a1 = cA + (size_t)(t + 1) * kstep;
;             const char* a2 = last ? nA : cA + (size_t)(t + 2) * kstep; const char* b2 = last ? nB : cB + (size_t)(t + 2) * kstep;
;             const char* a3 = a2 + kstep; const char* b3 = b2 + kstep;
;     ...
;         for (int a = 0; a < 2; ++a)
; #pragma unroll
;             for (int b = 0; b < 2; ++b)
; #pragma unroll
;                 for (int m = 0; m < 4; ++m)
; #pragma unroll
;                     for (int n = 0; n < 2; ++n) acc[a][b][m][n] = (f32x4){0.f, 0.f, 0.f, 0.f};
;         cur = nxt; cA = nA; cB = nB; ++ui;
.LBB0_1624:
	s_ashr_i32 s69, s68, 31
	s_lshl_b64 s[58:59], s[68:69], 19
	s_add_u32 s76, s72, s58
	s_addc_u32 s77, s73, s59
	s_ashr_i32 s63, s62, 31
	s_lshl_b64 s[58:59], s[62:63], 19
	s_add_u32 s80, s2, s58
	v_mov_b32_e32 v123, 0
	s_addc_u32 s81, s3, s59
	s_andn2_b64 vcc, exec, s[46:47]
	v_mov_b32_e32 v122, v123
	v_mov_b32_e32 v121, v123
	v_mov_b32_e32 v120, v123
	v_mov_b32_e32 v127, v123
	v_mov_b32_e32 v126, v123
	v_mov_b32_e32 v125, v123
	v_mov_b32_e32 v124, v123
	v_mov_b32_e32 v111, v123
	v_mov_b32_e32 v110, v123
	v_mov_b32_e32 v109, v123
	v_mov_b32_e32 v108, v123
	v_mov_b32_e32 v107, v123
	v_mov_b32_e32 v106, v123
	v_mov_b32_e32 v105, v123
	v_mov_b32_e32 v104, v123
	v_mov_b32_e32 v95, v123
	v_mov_b32_e32 v94, v123
	v_mov_b32_e32 v93, v123
	v_mov_b32_e32 v92, v123
	v_mov_b32_e32 v91, v123
	v_mov_b32_e32 v90, v123
	v_mov_b32_e32 v89, v123
	v_mov_b32_e32 v88, v123
	v_mov_b32_e32 v79, v123
	v_mov_b32_e32 v78, v123
	v_mov_b32_e32 v77, v123
	v_mov_b32_e32 v76, v123
	v_mov_b32_e32 v75, v123
	v_mov_b32_e32 v74, v123
	v_mov_b32_e32 v73, v123
	v_mov_b32_e32 v72, v123
	v_mov_b32_e32 v119, v123
	v_mov_b32_e32 v118, v123
	v_mov_b32_e32 v117, v123
	v_mov_b32_e32 v116, v123
	v_mov_b32_e32 v115, v123
	v_mov_b32_e32 v114, v123
	v_mov_b32_e32 v113, v123
	v_mov_b32_e32 v112, v123
	v_mov_b32_e32 v103, v123
	v_mov_b32_e32 v102, v123
	v_mov_b32_e32 v101, v123
	v_mov_b32_e32 v100, v123
	v_mov_b32_e32 v99, v123
	v_mov_b32_e32 v98, v123
	v_mov_b32_e32 v97, v123
	v_mov_b32_e32 v96, v123
	v_mov_b32_e32 v87, v123
	v_mov_b32_e32 v86, v123
	v_mov_b32_e32 v85, v123
	v_mov_b32_e32 v84, v123
	v_mov_b32_e32 v83, v123
	v_mov_b32_e32 v82, v123
	v_mov_b32_e32 v81, v123
	v_mov_b32_e32 v80, v123
	v_mov_b32_e32 v71, v123
	v_mov_b32_e32 v70, v123
	v_mov_b32_e32 v69, v123
	v_mov_b32_e32 v68, v123
	v_mov_b32_e32 v67, v123
	v_mov_b32_e32 v66, v123
	v_mov_b32_e32 v65, v123
	v_mov_b32_e32 v64, v123
	v_mov_b32_e32 v63, v123
	v_mov_b32_e32 v62, v123
	v_mov_b32_e32 v61, v123
	v_mov_b32_e32 v60, v123
	v_mov_b32_e32 v59, v123
	v_mov_b32_e32 v58, v123
	v_mov_b32_e32 v57, v123
	v_mov_b32_e32 v56, v123
	v_mov_b32_e32 v47, v123
	v_mov_b32_e32 v46, v123
	v_mov_b32_e32 v45, v123
	v_mov_b32_e32 v44, v123
	v_mov_b32_e32 v43, v123
	v_mov_b32_e32 v42, v123
	v_mov_b32_e32 v41, v123
	v_mov_b32_e32 v40, v123
	v_mov_b32_e32 v31, v123
	v_mov_b32_e32 v30, v123
	v_mov_b32_e32 v29, v123
	v_mov_b32_e32 v28, v123
	v_mov_b32_e32 v27, v123
	v_mov_b32_e32 v26, v123
	v_mov_b32_e32 v25, v123
	v_mov_b32_e32 v24, v123
	v_mov_b32_e32 v15, v123
	v_mov_b32_e32 v14, v123
	v_mov_b32_e32 v13, v123
	v_mov_b32_e32 v12, v123
	v_mov_b32_e32 v11, v123
	v_mov_b32_e32 v10, v123
	v_mov_b32_e32 v9, v123
	v_mov_b32_e32 v8, v123
	v_mov_b32_e32 v55, v123
	v_mov_b32_e32 v54, v123
	v_mov_b32_e32 v53, v123
	v_mov_b32_e32 v52, v123
	v_mov_b32_e32 v51, v123
	v_mov_b32_e32 v50, v123
	v_mov_b32_e32 v49, v123
	v_mov_b32_e32 v48, v123
	v_mov_b32_e32 v39, v123
	v_mov_b32_e32 v38, v123
	v_mov_b32_e32 v37, v123
	v_mov_b32_e32 v36, v123
	v_mov_b32_e32 v35, v123
	v_mov_b32_e32 v34, v123
	v_mov_b32_e32 v33, v123
	v_mov_b32_e32 v32, v123
	v_mov_b32_e32 v23, v123
	v_mov_b32_e32 v22, v123
	v_mov_b32_e32 v21, v123
	v_mov_b32_e32 v20, v123
	v_mov_b32_e32 v19, v123
	v_mov_b32_e32 v18, v123
	v_mov_b32_e32 v17, v123
	v_mov_b32_e32 v16, v123
	v_mov_b32_e32 v7, v123
	v_mov_b32_e32 v6, v123
	v_mov_b32_e32 v5, v123
	v_mov_b32_e32 v4, v123
	v_mov_b32_e32 v3, v123
	v_mov_b32_e32 v2, v123
	v_mov_b32_e32 v1, v123
	v_mov_b32_e32 v0, v123
	s_cbranch_vccnz .LBB0_1627
	s_and_b64 s[58:59], s[44:45], exec
	s_cselect_b32 s53, s77, s87
	s_cselect_b32 s58, s76, s86
	s_cselect_b32 s59, s81, s89
	s_cselect_b32 s61, s80, s88
	s_add_u32 s86, s86, 0x40080
	s_addc_u32 s87, s87, 0
	s_add_u32 s63, s88, 0x100
	v_mov_b32_e32 v0, 0
	s_addc_u32 s64, s89, 0
	s_mov_b32 s69, 0
	v_mov_b32_e32 v1, v0
	v_mov_b32_e32 v2, v0
	v_mov_b32_e32 v3, v0
	v_mov_b32_e32 v4, v0
	v_mov_b32_e32 v5, v0
	v_mov_b32_e32 v6, v0
	v_mov_b32_e32 v7, v0
	v_mov_b32_e32 v16, v0
	v_mov_b32_e32 v17, v0
	v_mov_b32_e32 v18, v0
	v_mov_b32_e32 v19, v0
	v_mov_b32_e32 v20, v0
	v_mov_b32_e32 v21, v0
	v_mov_b32_e32 v22, v0
	v_mov_b32_e32 v23, v0
	v_mov_b32_e32 v32, v0
	v_mov_b32_e32 v33, v0
	v_mov_b32_e32 v34, v0
	v_mov_b32_e32 v35, v0
	v_mov_b32_e32 v36, v0
	v_mov_b32_e32 v37, v0
	v_mov_b32_e32 v38, v0
	v_mov_b32_e32 v39, v0
	v_mov_b32_e32 v48, v0
	v_mov_b32_e32 v49, v0
	v_mov_b32_e32 v50, v0
	v_mov_b32_e32 v51, v0
	v_mov_b32_e32 v52, v0
	v_mov_b32_e32 v53, v0
	v_mov_b32_e32 v54, v0
	v_mov_b32_e32 v55, v0
	v_mov_b32_e32 v8, v0
	v_mov_b32_e32 v9, v0
	v_mov_b32_e32 v10, v0
	v_mov_b32_e32 v11, v0
	v_mov_b32_e32 v12, v0
	v_mov_b32_e32 v13, v0
	v_mov_b32_e32 v14, v0
	v_mov_b32_e32 v15, v0
	v_mov_b32_e32 v24, v0
	v_mov_b32_e32 v25, v0
	v_mov_b32_e32 v26, v0
	v_mov_b32_e32 v27, v0
	v_mov_b32_e32 v28, v0
	v_mov_b32_e32 v29, v0
	v_mov_b32_e32 v30, v0
	v_mov_b32_e32 v31, v0
	v_mov_b32_e32 v40, v0
	v_mov_b32_e32 v41, v0
	v_mov_b32_e32 v42, v0
	v_mov_b32_e32 v43, v0
	v_mov_b32_e32 v44, v0
	v_mov_b32_e32 v45, v0
	v_mov_b32_e32 v46, v0
	v_mov_b32_e32 v47, v0
	v_mov_b32_e32 v56, v0
	v_mov_b32_e32 v57, v0
	v_mov_b32_e32 v58, v0
	v_mov_b32_e32 v59, v0
	v_mov_b32_e32 v60, v0
	v_mov_b32_e32 v61, v0
	v_mov_b32_e32 v62, v0
	v_mov_b32_e32 v63, v0
	v_mov_b32_e32 v64, v0
	v_mov_b32_e32 v65, v0
	v_mov_b32_e32 v66, v0
	v_mov_b32_e32 v67, v0
	v_mov_b32_e32 v68, v0
	v_mov_b32_e32 v69, v0
	v_mov_b32_e32 v70, v0
	v_mov_b32_e32 v71, v0
	v_mov_b32_e32 v80, v0
	v_mov_b32_e32 v81, v0
	v_mov_b32_e32 v82, v0
	v_mov_b32_e32 v83, v0
	v_mov_b32_e32 v84, v0
	v_mov_b32_e32 v85, v0
	v_mov_b32_e32 v86, v0
	v_mov_b32_e32 v87, v0
	v_mov_b32_e32 v96, v0
	v_mov_b32_e32 v97, v0
	v_mov_b32_e32 v98, v0
	v_mov_b32_e32 v99, v0
	v_mov_b32_e32 v100, v0
	v_mov_b32_e32 v101, v0
	v_mov_b32_e32 v102, v0
	v_mov_b32_e32 v103, v0
	v_mov_b32_e32 v112, v0
	v_mov_b32_e32 v113, v0
	v_mov_b32_e32 v114, v0
	v_mov_b32_e32 v115, v0
	v_mov_b32_e32 v116, v0
	v_mov_b32_e32 v117, v0
	v_mov_b32_e32 v118, v0
	v_mov_b32_e32 v119, v0
	v_mov_b32_e32 v72, v0
	v_mov_b32_e32 v73, v0
	v_mov_b32_e32 v74, v0
	v_mov_b32_e32 v75, v0
	v_mov_b32_e32 v76, v0
	v_mov_b32_e32 v77, v0
	v_mov_b32_e32 v78, v0
	v_mov_b32_e32 v79, v0
	v_mov_b32_e32 v88, v0
	v_mov_b32_e32 v89, v0
	v_mov_b32_e32 v90, v0
	v_mov_b32_e32 v91, v0
	v_mov_b32_e32 v92, v0
	v_mov_b32_e32 v93, v0
	v_mov_b32_e32 v94, v0
	v_mov_b32_e32 v95, v0
	v_mov_b32_e32 v104, v0
	v_mov_b32_e32 v105, v0
	v_mov_b32_e32 v106, v0
	v_mov_b32_e32 v107, v0
	v_mov_b32_e32 v108, v0
	v_mov_b32_e32 v109, v0
	v_mov_b32_e32 v110, v0
	v_mov_b32_e32 v111, v0
	v_mov_b32_e32 v124, v0
	v_mov_b32_e32 v125, v0
	v_mov_b32_e32 v126, v0
	v_mov_b32_e32 v127, v0
	v_mov_b32_e32 v120, v0
	v_mov_b32_e32 v121, v0
	v_mov_b32_e32 v122, v0
	v_mov_b32_e32 v123, v0
	.p2alignl 6, 3212836864

;     __device__ __forceinline__ size_t aoff(const Unit& u, size_t ts, int) const { return (size_t)u.pm * ts; }
;     __device__ __forceinline__ size_t boff(const Unit& u, size_t ts, int) const { return (size_t)u.pn * ts; }
;     __device__ __forceinline__ size_t aoff(const Unit& u, size_t ts, int K) const { return (size_t)(u.pm & 15) * ts + (size_t)(u.pm >> 4) * K * 2; }
;     __device__ __forceinline__ size_t boff(const Unit& u, size_t ts, int K) const { return (size_t)u.pn * ts + (size_t)(u.pm >> 4) * K * 2; }
; template <class Epi, class Sched, bool ALIGN_EPI = false, bool SP2 = false>
; __device__ __forceinline__ void gemm_phase(PG8_LAS unsigned char* lds, const Gemm g, const Sched& S, const Epi& E) {
;     ...
;         const bool has_next = S.next(ui + 1, nxt);
;         const char* nA = has_next ? (const char*)g.A + S.aoff(nxt, tstepA, K) : cA; const char* nB = has_next ? (const char*)g.Bt + S.boff(nxt, tstepB, K) : cB;
;         for (int t = 0; t < nt; t += 2) {
;             const bool last = (t == nt - 2);
;             const char* a1 = cA + (size_t)(t + 1) * kstep;
;             const char* a2 = last ? nA : cA + (size_t)(t + 2) * kstep; const char* b2 = last ? nB : cB + (size_t)(t + 2) * kstep;
;             const char* a3 = a2 + kstep; const char* b3 = b2 + kstep;
;     ...
;         for (int a = 0; a < 2; ++a)
; #pragma unroll
;             for (int b = 0; b < 2; ++b)
; #pragma unroll
;                 for (int m = 0; m < 4; ++m)
; #pragma unroll
;                     for (int n = 0; n < 2; ++n) acc[a][b][m][n] = (f32x4){0.f, 0.f, 0.f, 0.f};
;         cur = nxt; cA = nA; cB = nB; ++ui;
.LBB0_1697:
	s_ashr_i32 s47, s46, 31
	s_lshl_b64 s[48:49], s[46:47], 21
	s_add_u32 s48, s30, s48
	s_addc_u32 s49, s31, s49
	s_ashr_i32 s45, s44, 31
	s_lshl_b64 s[52:53], s[44:45], 21
	s_add_u32 s52, s55, s52
	v_mov_b32_e32 v159, 0
	s_addc_u32 s53, s61, s53
	s_andn2_b64 vcc, exec, s[34:35]
	v_mov_b32_e32 v158, v159
	v_mov_b32_e32 v161, v159
	v_mov_b32_e32 v160, v159
	v_mov_b32_e32 v163, v159
	v_mov_b32_e32 v162, v159
	v_mov_b32_e32 v165, v159
	v_mov_b32_e32 v164, v159
	v_mov_b32_e32 v151, v159
	v_mov_b32_e32 v150, v159
	v_mov_b32_e32 v153, v159
	v_mov_b32_e32 v152, v159
	v_mov_b32_e32 v155, v159
	v_mov_b32_e32 v154, v159
	v_mov_b32_e32 v157, v159
	v_mov_b32_e32 v156, v159
	v_mov_b32_e32 v143, v159
	v_mov_b32_e32 v142, v159
	v_mov_b32_e32 v145, v159
	v_mov_b32_e32 v144, v159
	v_mov_b32_e32 v147, v159
	v_mov_b32_e32 v146, v159
	v_mov_b32_e32 v149, v159
	v_mov_b32_e32 v148, v159
	v_mov_b32_e32 v125, v159
	v_mov_b32_e32 v124, v159
	v_mov_b32_e32 v127, v159
	v_mov_b32_e32 v126, v159
	v_mov_b32_e32 v139, v159
	v_mov_b32_e32 v138, v159
	v_mov_b32_e32 v141, v159
	v_mov_b32_e32 v140, v159
	v_mov_b32_e32 v73, v159
	v_mov_b32_e32 v72, v159
	v_mov_b32_e32 v75, v159
	v_mov_b32_e32 v74, v159
	v_mov_b32_e32 v81, v159
	v_mov_b32_e32 v80, v159
	v_mov_b32_e32 v83, v159
	v_mov_b32_e32 v82, v159
	v_mov_b32_e32 v57, v159
	v_mov_b32_e32 v56, v159
	v_mov_b32_e32 v59, v159
	v_mov_b32_e32 v58, v159
	v_mov_b32_e32 v65, v159
	v_mov_b32_e32 v64, v159
	v_mov_b32_e32 v67, v159
	v_mov_b32_e32 v66, v159
	v_mov_b32_e32 v49, v159
	v_mov_b32_e32 v48, v159
	v_mov_b32_e32 v51, v159
	v_mov_b32_e32 v50, v159
	v_mov_b32_e32 v55, v159
	v_mov_b32_e32 v54, v159
	v_mov_b32_e32 v53, v159
	v_mov_b32_e32 v52, v159
	v_mov_b32_e32 v41, v159
	v_mov_b32_e32 v40, v159
	v_mov_b32_e32 v43, v159
	v_mov_b32_e32 v42, v159
	v_mov_b32_e32 v45, v159
	v_mov_b32_e32 v44, v159
	v_mov_b32_e32 v47, v159
	v_mov_b32_e32 v46, v159
	v_mov_b32_e32 v117, v159
	v_mov_b32_e32 v116, v159
	v_mov_b32_e32 v119, v159
	v_mov_b32_e32 v118, v159
	v_mov_b32_e32 v121, v159
	v_mov_b32_e32 v120, v159
	v_mov_b32_e32 v123, v159
	v_mov_b32_e32 v122, v159
	v_mov_b32_e32 v109, v159
	v_mov_b32_e32 v108, v159
	v_mov_b32_e32 v111, v159
	v_mov_b32_e32 v110, v159
	v_mov_b32_e32 v113, v159
	v_mov_b32_e32 v112, v159
	v_mov_b32_e32 v115, v159
	v_mov_b32_e32 v114, v159
	v_mov_b32_e32 v101, v159
	v_mov_b32_e32 v100, v159
	v_mov_b32_e32 v103, v159
	v_mov_b32_e32 v102, v159
	v_mov_b32_e32 v105, v159
	v_mov_b32_e32 v104, v159
	v_mov_b32_e32 v107, v159
	v_mov_b32_e32 v106, v159
	v_mov_b32_e32 v89, v159
	v_mov_b32_e32 v88, v159
	v_mov_b32_e32 v91, v159
	v_mov_b32_e32 v90, v159
	v_mov_b32_e32 v97, v159
	v_mov_b32_e32 v96, v159
	v_mov_b32_e32 v99, v159
	v_mov_b32_e32 v98, v159
	v_mov_b32_e32 v33, v159
	v_mov_b32_e32 v32, v159
	v_mov_b32_e32 v35, v159
	v_mov_b32_e32 v34, v159
	v_mov_b32_e32 v37, v159
	v_mov_b32_e32 v36, v159
	v_mov_b32_e32 v39, v159
	v_mov_b32_e32 v38, v159
	v_mov_b32_e32 v25, v159
	v_mov_b32_e32 v24, v159
	v_mov_b32_e32 v27, v159
	v_mov_b32_e32 v26, v159
	v_mov_b32_e32 v29, v159
	v_mov_b32_e32 v28, v159
	v_mov_b32_e32 v31, v159
	v_mov_b32_e32 v30, v159
	v_mov_b32_e32 v21, v159
	v_mov_b32_e32 v20, v159
	v_mov_b32_e32 v23, v159
	v_mov_b32_e32 v22, v159
	v_mov_b32_e32 v11, v159
	v_mov_b32_e32 v10, v159
	v_mov_b32_e32 v9, v159
	v_mov_b32_e32 v8, v159
	v_mov_b32_e32 v19, v159
	v_mov_b32_e32 v18, v159
	v_mov_b32_e32 v17, v159
	v_mov_b32_e32 v16, v159
	v_mov_b32_e32 v15, v159
	v_mov_b32_e32 v14, v159
	v_mov_b32_e32 v13, v159
	v_mov_b32_e32 v12, v159
	s_cbranch_vccnz .LBB0_1701
	s_and_b64 s[76:77], s[42:43], exec
	s_cselect_b32 s45, s49, s63
	s_cselect_b32 s47, s48, s62
	s_cselect_b32 s59, s53, s69
	s_cselect_b32 s64, s52, s68
	s_add_u32 s62, s62, 0x100080
	s_addc_u32 s63, s63, 0
	s_add_u32 s78, s68, 0x100
	v_mov_b32_e32 v0, 0
	s_addc_u32 s79, s69, 0
	s_mov_b32 s68, 0
	v_mov_b32_e32 v1, v0
	v_mov_b32_e32 v2, v0
	v_mov_b32_e32 v3, v0
	v_mov_b32_e32 v4, v0
	v_mov_b32_e32 v5, v0
	v_mov_b32_e32 v6, v0
	v_mov_b32_e32 v7, v0
	v_mov_b32_e32 v8, v0
	v_mov_b32_e32 v9, v0
	v_mov_b32_e32 v10, v0
	v_mov_b32_e32 v11, v0
	v_mov_b32_e32 v12, v0
	v_mov_b32_e32 v13, v0
	v_mov_b32_e32 v14, v0
	v_mov_b32_e32 v15, v0
	v_mov_b32_e32 v16, v0
	v_mov_b32_e32 v17, v0
	v_mov_b32_e32 v18, v0
	v_mov_b32_e32 v19, v0
	v_mov_b32_e32 v20, v0
	v_mov_b32_e32 v21, v0
	v_mov_b32_e32 v22, v0
	v_mov_b32_e32 v23, v0
	v_mov_b32_e32 v24, v0
	v_mov_b32_e32 v25, v0
	v_mov_b32_e32 v26, v0
	v_mov_b32_e32 v27, v0
	v_mov_b32_e32 v28, v0
	v_mov_b32_e32 v29, v0
	v_mov_b32_e32 v30, v0
	v_mov_b32_e32 v31, v0
	v_mov_b32_e32 v32, v0
	v_mov_b32_e32 v33, v0
	v_mov_b32_e32 v34, v0
	v_mov_b32_e32 v35, v0
	v_mov_b32_e32 v40, v0
	v_mov_b32_e32 v41, v0
	v_mov_b32_e32 v42, v0
	v_mov_b32_e32 v43, v0
	v_mov_b32_e32 v48, v0
	v_mov_b32_e32 v49, v0
	v_mov_b32_e32 v50, v0
	v_mov_b32_e32 v51, v0
	v_mov_b32_e32 v56, v0
	v_mov_b32_e32 v57, v0
	v_mov_b32_e32 v58, v0
	v_mov_b32_e32 v59, v0
	v_mov_b32_e32 v64, v0
	v_mov_b32_e32 v65, v0
	v_mov_b32_e32 v66, v0
	v_mov_b32_e32 v67, v0
	v_mov_b32_e32 v72, v0
	v_mov_b32_e32 v73, v0
	v_mov_b32_e32 v74, v0
	v_mov_b32_e32 v75, v0
	v_mov_b32_e32 v80, v0
	v_mov_b32_e32 v81, v0
	v_mov_b32_e32 v82, v0
	v_mov_b32_e32 v83, v0
	v_mov_b32_e32 v88, v0
	v_mov_b32_e32 v89, v0
	v_mov_b32_e32 v90, v0
	v_mov_b32_e32 v91, v0
	v_mov_b32_e32 v36, v0
	v_mov_b32_e32 v37, v0
	v_mov_b32_e32 v38, v0
	v_mov_b32_e32 v39, v0
	v_mov_b32_e32 v44, v0
	v_mov_b32_e32 v45, v0
	v_mov_b32_e32 v46, v0
	v_mov_b32_e32 v47, v0
	v_mov_b32_e32 v52, v0
	v_mov_b32_e32 v53, v0
	v_mov_b32_e32 v54, v0
	v_mov_b32_e32 v55, v0
	v_mov_b32_e32 v60, v0
	v_mov_b32_e32 v61, v0
	v_mov_b32_e32 v62, v0
	v_mov_b32_e32 v63, v0
	v_mov_b32_e32 v68, v0
	v_mov_b32_e32 v69, v0
	v_mov_b32_e32 v70, v0
	v_mov_b32_e32 v71, v0
	v_mov_b32_e32 v76, v0
	v_mov_b32_e32 v77, v0
	v_mov_b32_e32 v78, v0
	v_mov_b32_e32 v79, v0
	v_mov_b32_e32 v84, v0
	v_mov_b32_e32 v85, v0
	v_mov_b32_e32 v86, v0
	v_mov_b32_e32 v87, v0
	v_mov_b32_e32 v92, v0
	v_mov_b32_e32 v93, v0
	v_mov_b32_e32 v94, v0
	v_mov_b32_e32 v95, v0
	v_mov_b32_e32 v96, v0
	v_mov_b32_e32 v97, v0
	v_mov_b32_e32 v98, v0
	v_mov_b32_e32 v99, v0
	v_mov_b32_e32 v100, v0
	v_mov_b32_e32 v101, v0
	v_mov_b32_e32 v102, v0
	v_mov_b32_e32 v103, v0
	v_mov_b32_e32 v104, v0
	v_mov_b32_e32 v105, v0
	v_mov_b32_e32 v106, v0
	v_mov_b32_e32 v107, v0
	v_mov_b32_e32 v108, v0
	v_mov_b32_e32 v109, v0
	v_mov_b32_e32 v110, v0
	v_mov_b32_e32 v111, v0
	v_mov_b32_e32 v112, v0
	v_mov_b32_e32 v113, v0
	v_mov_b32_e32 v114, v0
	v_mov_b32_e32 v115, v0
	v_mov_b32_e32 v116, v0
	v_mov_b32_e32 v117, v0
	v_mov_b32_e32 v118, v0
	v_mov_b32_e32 v119, v0
	v_mov_b32_e32 v120, v0
	v_mov_b32_e32 v121, v0
	v_mov_b32_e32 v122, v0
	v_mov_b32_e32 v123, v0
	v_mov_b32_e32 v124, v0
	v_mov_b32_e32 v125, v0
	v_mov_b32_e32 v126, v0
	v_mov_b32_e32 v127, v0
	.p2alignl 6, 3212836864

; template <class Epi, class Sched, bool ALIGN_EPI = false, bool SP2 = false>
; __device__ __forceinline__ void gemm_phase(PG8_LAS unsigned char* lds, const Gemm g, const Sched& S, const Epi& E) {
;     ...
;         for (int t = 0; t < nt; t += 2) {
;             const bool last = (t == nt - 2);
;             const char* a1 = cA + (size_t)(t + 1) * kstep;
;             const char* a2 = last ? nA : cA + (size_t)(t + 2) * kstep; const char* b2 = last ? nB : cB + (size_t)(t + 2) * kstep;
;             const char* a3 = a2 + kstep; const char* b3 = b2 + kstep;
;     ...
;         for (int a = 0; a < 2; ++a)
; #pragma unroll
;             for (int b = 0; b < 2; ++b)
; #pragma unroll
;                 for (int m = 0; m < 4; ++m)
; #pragma unroll
;                     for (int n = 0; n < 2; ++n) acc[a][b][m][n] = (f32x4){0.f, 0.f, 0.f, 0.f};
;         cur = nxt; cA = nA; cB = nB; ++ui;
.LBB0_1724:
	v_mov_b32_e32 v127, 0
	s_andn2_b64 vcc, exec, s[34:35]
	v_mov_b32_e32 v126, 0
	v_mov_b32_e32 v125, 0
	v_mov_b32_e32 v124, 0
	v_mov_b32_e32 v123, 0
	v_mov_b32_e32 v122, 0
	v_mov_b32_e32 v121, 0
	v_mov_b32_e32 v120, 0
	v_mov_b32_e32 v119, 0
	v_mov_b32_e32 v118, 0
	v_mov_b32_e32 v117, 0
	v_mov_b32_e32 v116, 0
	v_mov_b32_e32 v115, 0
	v_mov_b32_e32 v114, 0
	v_mov_b32_e32 v113, 0
	v_mov_b32_e32 v112, 0
	v_mov_b32_e32 v111, 0
	v_mov_b32_e32 v110, 0
	v_mov_b32_e32 v109, 0
	v_mov_b32_e32 v108, 0
	v_mov_b32_e32 v107, 0
	v_mov_b32_e32 v106, 0
	v_mov_b32_e32 v105, 0
	v_mov_b32_e32 v104, 0
	v_mov_b32_e32 v103, 0
	v_mov_b32_e32 v102, 0
	v_mov_b32_e32 v101, 0
	v_mov_b32_e32 v100, 0
	v_mov_b32_e32 v99, 0
	v_mov_b32_e32 v98, 0
	v_mov_b32_e32 v97, 0
	v_mov_b32_e32 v96, 0
	v_mov_b32_e32 v91, 0
	v_mov_b32_e32 v90, 0
	v_mov_b32_e32 v89, 0
	v_mov_b32_e32 v88, 0
	v_mov_b32_e32 v83, 0
	v_mov_b32_e32 v82, 0
	v_mov_b32_e32 v81, 0
	v_mov_b32_e32 v80, 0
	v_mov_b32_e32 v75, 0
	v_mov_b32_e32 v74, 0
	v_mov_b32_e32 v73, 0
	v_mov_b32_e32 v72, 0
	v_mov_b32_e32 v67, 0
	v_mov_b32_e32 v66, 0
	v_mov_b32_e32 v65, 0
	v_mov_b32_e32 v64, 0
	v_mov_b32_e32 v59, 0
	v_mov_b32_e32 v58, 0
	v_mov_b32_e32 v57, 0
	v_mov_b32_e32 v56, 0
	v_mov_b32_e32 v51, 0
	v_mov_b32_e32 v50, 0
	v_mov_b32_e32 v49, 0
	v_mov_b32_e32 v48, 0
	v_mov_b32_e32 v43, 0
	v_mov_b32_e32 v42, 0
	v_mov_b32_e32 v41, 0
	v_mov_b32_e32 v40, 0
	v_mov_b32_e32 v35, 0
	v_mov_b32_e32 v34, 0
	v_mov_b32_e32 v33, 0
	v_mov_b32_e32 v32, 0
	v_mov_b32_e32 v141, 0
	v_mov_b32_e32 v140, 0
	v_mov_b32_e32 v145, 0
	v_mov_b32_e32 v144, 0
	v_mov_b32_e32 v139, 0
	v_mov_b32_e32 v138, 0
	v_mov_b32_e32 v143, 0
	v_mov_b32_e32 v142, 0
	v_mov_b32_e32 v149, 0
	v_mov_b32_e32 v148, 0
	v_mov_b32_e32 v153, 0
	v_mov_b32_e32 v152, 0
	v_mov_b32_e32 v147, 0
	v_mov_b32_e32 v146, 0
	v_mov_b32_e32 v151, 0
	v_mov_b32_e32 v150, 0
	v_mov_b32_e32 v157, 0
	v_mov_b32_e32 v156, 0
	v_mov_b32_e32 v161, 0
	v_mov_b32_e32 v160, 0
	v_mov_b32_e32 v155, 0
	v_mov_b32_e32 v154, 0
	v_mov_b32_e32 v159, 0
	v_mov_b32_e32 v158, 0
	v_mov_b32_e32 v163, 0
	v_mov_b32_e32 v162, 0
	v_mov_b32_e32 v167, 0
	v_mov_b32_e32 v166, 0
	v_mov_b32_e32 v165, 0
	v_mov_b32_e32 v164, 0
	v_mov_b32_e32 v169, 0
	v_mov_b32_e32 v168, 0
	v_mov_b32_e32 v47, 0
	v_mov_b32_e32 v46, 0
	v_mov_b32_e32 v45, 0
	v_mov_b32_e32 v44, 0
	v_mov_b32_e32 v39, 0
	v_mov_b32_e32 v38, 0
	v_mov_b32_e32 v37, 0
	v_mov_b32_e32 v36, 0
	v_mov_b32_e32 v31, 0
	v_mov_b32_e32 v30, 0
	v_mov_b32_e32 v29, 0
	v_mov_b32_e32 v28, 0
	v_mov_b32_e32 v27, 0
	v_mov_b32_e32 v26, 0
	v_mov_b32_e32 v25, 0
	v_mov_b32_e32 v24, 0
	v_mov_b32_e32 v23, 0
	v_mov_b32_e32 v22, 0
	v_mov_b32_e32 v21, 0
	v_mov_b32_e32 v20, 0
	v_mov_b32_e32 v19, 0
	v_mov_b32_e32 v18, 0
	v_mov_b32_e32 v17, 0
	v_mov_b32_e32 v16, 0
	v_mov_b32_e32 v15, 0
	v_mov_b32_e32 v14, 0
	v_mov_b32_e32 v13, 0
	v_mov_b32_e32 v12, 0
	v_mov_b32_e32 v11, 0
	v_mov_b32_e32 v10, 0
	v_mov_b32_e32 v9, 0
	v_mov_b32_e32 v8, 0
	s_cbranch_vccnz .LBB0_1728
	s_add_u32 s52, s52, 0x100080
	s_addc_u32 s53, s53, 0
	s_add_u32 s47, s62, 0x100
	v_mov_b32_e32 v0, 0
	s_addc_u32 s58, s63, 0
	s_mov_b32 s59, 0
	v_mov_b32_e32 v1, v0
	v_mov_b32_e32 v2, v0
	v_mov_b32_e32 v3, v0
	v_mov_b32_e32 v4, v0
	v_mov_b32_e32 v5, v0
	v_mov_b32_e32 v6, v0
	v_mov_b32_e32 v7, v0
	v_mov_b32_e32 v8, v0
	v_mov_b32_e32 v9, v0
	v_mov_b32_e32 v10, v0
	v_mov_b32_e32 v11, v0
	v_mov_b32_e32 v12, v0
	v_mov_b32_e32 v13, v0
	v_mov_b32_e32 v14, v0
	v_mov_b32_e32 v15, v0
	v_mov_b32_e32 v16, v0
	v_mov_b32_e32 v17, v0
	v_mov_b32_e32 v18, v0
	v_mov_b32_e32 v19, v0
	v_mov_b32_e32 v20, v0
	v_mov_b32_e32 v21, v0
	v_mov_b32_e32 v22, v0
	v_mov_b32_e32 v23, v0
	v_mov_b32_e32 v24, v0
	v_mov_b32_e32 v25, v0
	v_mov_b32_e32 v26, v0
	v_mov_b32_e32 v27, v0
	v_mov_b32_e32 v28, v0
	v_mov_b32_e32 v29, v0
	v_mov_b32_e32 v30, v0
	v_mov_b32_e32 v31, v0
	v_mov_b32_e32 v32, v0
	v_mov_b32_e32 v33, v0
	v_mov_b32_e32 v34, v0
	v_mov_b32_e32 v35, v0
	v_mov_b32_e32 v40, v0
	v_mov_b32_e32 v41, v0
	v_mov_b32_e32 v42, v0
	v_mov_b32_e32 v43, v0
	v_mov_b32_e32 v48, v0
	v_mov_b32_e32 v49, v0
	v_mov_b32_e32 v50, v0
	v_mov_b32_e32 v51, v0
	v_mov_b32_e32 v56, v0
	v_mov_b32_e32 v57, v0
	v_mov_b32_e32 v58, v0
	v_mov_b32_e32 v59, v0
	v_mov_b32_e32 v64, v0
	v_mov_b32_e32 v65, v0
	v_mov_b32_e32 v66, v0
	v_mov_b32_e32 v67, v0
	v_mov_b32_e32 v72, v0
	v_mov_b32_e32 v73, v0
	v_mov_b32_e32 v74, v0
	v_mov_b32_e32 v75, v0
	v_mov_b32_e32 v80, v0
	v_mov_b32_e32 v81, v0
	v_mov_b32_e32 v82, v0
	v_mov_b32_e32 v83, v0
	v_mov_b32_e32 v88, v0
	v_mov_b32_e32 v89, v0
	v_mov_b32_e32 v90, v0
	v_mov_b32_e32 v91, v0
	v_mov_b32_e32 v36, v0
	v_mov_b32_e32 v37, v0
	v_mov_b32_e32 v38, v0
	v_mov_b32_e32 v39, v0
	v_mov_b32_e32 v44, v0
	v_mov_b32_e32 v45, v0
	v_mov_b32_e32 v46, v0
	v_mov_b32_e32 v47, v0
	v_mov_b32_e32 v52, v0
	v_mov_b32_e32 v53, v0
	v_mov_b32_e32 v54, v0
	v_mov_b32_e32 v55, v0
	v_mov_b32_e32 v60, v0
	v_mov_b32_e32 v61, v0
	v_mov_b32_e32 v62, v0
	v_mov_b32_e32 v63, v0
	v_mov_b32_e32 v68, v0
	v_mov_b32_e32 v69, v0
	v_mov_b32_e32 v70, v0
	v_mov_b32_e32 v71, v0
	v_mov_b32_e32 v76, v0
	v_mov_b32_e32 v77, v0
	v_mov_b32_e32 v78, v0
	v_mov_b32_e32 v79, v0
	v_mov_b32_e32 v84, v0
	v_mov_b32_e32 v85, v0
	v_mov_b32_e32 v86, v0
	v_mov_b32_e32 v87, v0
	v_mov_b32_e32 v92, v0
	v_mov_b32_e32 v93, v0
	v_mov_b32_e32 v94, v0
	v_mov_b32_e32 v95, v0
	v_mov_b32_e32 v96, v0
	v_mov_b32_e32 v97, v0
	v_mov_b32_e32 v98, v0
	v_mov_b32_e32 v99, v0
	v_mov_b32_e32 v100, v0
	v_mov_b32_e32 v101, v0
	v_mov_b32_e32 v102, v0
	v_mov_b32_e32 v103, v0
	v_mov_b32_e32 v104, v0
	v_mov_b32_e32 v105, v0
	v_mov_b32_e32 v106, v0
	v_mov_b32_e32 v107, v0
	v_mov_b32_e32 v108, v0
	v_mov_b32_e32 v109, v0
	v_mov_b32_e32 v110, v0
	v_mov_b32_e32 v111, v0
	v_mov_b32_e32 v112, v0
	v_mov_b32_e32 v113, v0
	v_mov_b32_e32 v114, v0
	v_mov_b32_e32 v115, v0
	v_mov_b32_e32 v116, v0
	v_mov_b32_e32 v117, v0
	v_mov_b32_e32 v118, v0
	v_mov_b32_e32 v119, v0
	v_mov_b32_e32 v120, v0
	v_mov_b32_e32 v121, v0
	v_mov_b32_e32 v122, v0
	v_mov_b32_e32 v123, v0
	v_mov_b32_e32 v124, v0
	v_mov_b32_e32 v125, v0
	v_mov_b32_e32 v126, v0
	v_mov_b32_e32 v127, v0
	.p2alignl 6, 3212836864
